# attention PV blocks rewritten without register shuffling (19 v_mov, 7 address adds, 8 redundant max removed); w_o/mlp2 residual epilogue: x/gate loads batched and pipelined per 16-row group instead of
# speedup vs baseline: 1.1343x; 1.0161x over previous
; template <int MI, int NI>
; DI void gemm256(f32x4 (&acc)[MI][NI], const u16* __restrict__ A, int lda, const u16* __restrict__ Bt, int ldb, int K, int m0, int n0, char* smem) {
;     ...
;   const int nk = K >> 5;
;   G256_ISSUE(0, 0);
;   if (nk > 1) G256_ISSUE(1, 32);
;   const int foff = lr * 64 + ((lq ^ ((lr >> 3) << 1)) * 16);
;   int st = 0;
;   for (int kt = 0; kt < nk; ++kt) {
;     if (kt + 1 < nk) asm volatile("s_waitcnt vmcnt(%0) lgkmcnt(0)" :: "n"(LPS) : "memory");
;     else asm volatile("s_waitcnt vmcnt(0) lgkmcnt(0)" ::: "memory");
;     __builtin_amdgcn_s_barrier();
;     __builtin_amdgcn_s_setprio(1);
;     const char* sb = smem + st * STAGE + foff;
;     bf16x8 af[MI], bfr[NI];
; #pragma unroll
;     for (int mi = 0; mi < MI; ++mi) af[mi] = *(const bf16x8*)(sb + (wr * MI + mi) * 1024);
; #pragma unroll
;     for (int ni = 0; ni < NI; ++ni) bfr[ni] = *(const bf16x8*)(sb + ABYTES + (wc * NI + ni) * 1024);
;     __builtin_amdgcn_sched_barrier(0x0);
;     if (kt + 2 < nk) { const int s2 = st >= 1 ? st - 1 : 2; G256_ISSUE(s2, (kt + 2) * 32); }
;     __builtin_amdgcn_s_setprio(0);
; #pragma unroll
;     for (int mi = 0; mi < MI; ++mi)
; #pragma unroll
;       for (int ni = 0; ni < NI; ++ni)
;         acc[mi][ni] = __builtin_amdgcn_mfma_f32_16x16x32_bf16(bfr[ni], af[mi], acc[mi][ni], 0, 0, 0);
;     st = st == 2 ? 0 : st + 1;
;   }
.Lpipe_wo:
	v_add_u32_e32 v161, s12, v160
	ds_read_b128 v[156:159], v161 offset:4096
	ds_read_b128 v[164:167], v161 offset:5120
	ds_read_b128 v[168:171], v161 offset:6144
	ds_read_b128 v[172:175], v161 offset:7168
	s_add_i32 s14, s12, 0xffffa000
	s_cmp_eq_u32 s12, 0
	s_cselect_b32 s14, 0xc000, s14
	s_add_i32 s15, s14, s13
	s_add_i32 s14, s14, s4
	s_mov_b32 m0, s15
	s_waitcnt lgkmcnt(7)
	v_mfma_f32_16x16x32_bf16 v[126:129], v[176:179], v[140:143], v[126:129]
	global_load_lds_dwordx4 v[196:197], off
	v_mfma_f32_16x16x32_bf16 v[110:113], v[176:179], v[144:147], v[110:113]
	v_lshl_add_u64 v[196:197], v[196:197], 0, s[98:99]
	s_add_i32 m0, s15, 0x400
	v_mfma_f32_16x16x32_bf16 v[94:97], v[176:179], v[148:151], v[94:97]
	global_load_lds_dwordx4 v[198:199], off
	v_mfma_f32_16x16x32_bf16 v[78:81], v[176:179], v[152:155], v[78:81]
	v_lshl_add_u64 v[198:199], v[198:199], 0, s[98:99]
	s_add_i32 m0, s15, 0x800
	s_waitcnt lgkmcnt(6)
	v_mfma_f32_16x16x32_bf16 v[122:125], v[180:183], v[140:143], v[122:125]
	global_load_lds_dwordx4 v[200:201], off
	v_mfma_f32_16x16x32_bf16 v[106:109], v[180:183], v[144:147], v[106:109]
	v_lshl_add_u64 v[200:201], v[200:201], 0, s[98:99]
	s_add_i32 m0, s15, 0xc00
	v_mfma_f32_16x16x32_bf16 v[90:93], v[180:183], v[148:151], v[90:93]
	global_load_lds_dwordx4 v[202:203], off
	v_mfma_f32_16x16x32_bf16 v[74:77], v[180:183], v[152:155], v[74:77]
	v_lshl_add_u64 v[202:203], v[202:203], 0, s[98:99]
	s_mov_b32 m0, s14
	s_waitcnt lgkmcnt(5)
	v_mfma_f32_16x16x32_bf16 v[118:121], v[184:187], v[140:143], v[118:121]
	global_load_lds_dwordx4 v[204:205], off
	v_mfma_f32_16x16x32_bf16 v[102:105], v[184:187], v[144:147], v[102:105]
	v_lshl_add_u64 v[204:205], v[204:205], 0, 64
	s_add_i32 m0, s14, 0x400
	v_mfma_f32_16x16x32_bf16 v[86:89], v[184:187], v[148:151], v[86:89]
	global_load_lds_dwordx4 v[206:207], off
	v_mfma_f32_16x16x32_bf16 v[70:73], v[184:187], v[152:155], v[70:73]
	v_lshl_add_u64 v[206:207], v[206:207], 0, 64
	s_waitcnt lgkmcnt(4)
	v_mfma_f32_16x16x32_bf16 v[114:117], v[188:191], v[140:143], v[114:117]
	v_mfma_f32_16x16x32_bf16 v[98:101], v[188:191], v[144:147], v[98:101]
	v_mfma_f32_16x16x32_bf16 v[82:85], v[188:191], v[148:151], v[82:85]
	v_mfma_f32_16x16x32_bf16 v[66:69], v[188:191], v[152:155], v[66:69]
	s_waitcnt vmcnt(6) lgkmcnt(0)
	s_barrier
	s_add_i32 s15, s12, 0x6000
	s_cmp_eq_u32 s12, 0xc000
	s_cselect_b32 s12, 0, s15
	v_add_u32_e32 v192, s12, v160
	v_add_u32_e32 v193, s12, v0
	v_mfma_f32_16x16x32_bf16 v[62:65], v[176:179], v[156:159], v[62:65]
	ds_read_b128 v[140:143], v192
	v_mfma_f32_16x16x32_bf16 v[46:49], v[176:179], v[164:167], v[46:49]
	ds_read_b128 v[144:147], v192 offset:1024
	v_mfma_f32_16x16x32_bf16 v[30:33], v[176:179], v[168:171], v[30:33]
	ds_read_b128 v[148:151], v192 offset:2048
	v_mfma_f32_16x16x32_bf16 v[14:17], v[176:179], v[172:175], v[14:17]
	ds_read_b128 v[152:155], v192 offset:3072
	ds_read_b128 v[176:179], v193 offset:16384
	v_mfma_f32_16x16x32_bf16 v[58:61], v[180:183], v[156:159], v[58:61]
	v_mfma_f32_16x16x32_bf16 v[42:45], v[180:183], v[164:167], v[42:45]
	v_mfma_f32_16x16x32_bf16 v[26:29], v[180:183], v[168:171], v[26:29]
	v_mfma_f32_16x16x32_bf16 v[10:13], v[180:183], v[172:175], v[10:13]
	ds_read_b128 v[180:183], v193 offset:17408
	v_mfma_f32_16x16x32_bf16 v[54:57], v[184:187], v[156:159], v[54:57]
	v_mfma_f32_16x16x32_bf16 v[38:41], v[184:187], v[164:167], v[38:41]
	v_mfma_f32_16x16x32_bf16 v[22:25], v[184:187], v[168:171], v[22:25]
	v_mfma_f32_16x16x32_bf16 v[6:9], v[184:187], v[172:175], v[6:9]
	ds_read_b128 v[184:187], v193 offset:18432
	v_mfma_f32_16x16x32_bf16 v[50:53], v[188:191], v[156:159], v[50:53]
	v_mfma_f32_16x16x32_bf16 v[34:37], v[188:191], v[164:167], v[34:37]
	v_mfma_f32_16x16x32_bf16 v[18:21], v[188:191], v[168:171], v[18:21]
	v_mfma_f32_16x16x32_bf16 v[2:5], v[188:191], v[172:175], v[2:5]
	ds_read_b128 v[188:191], v193 offset:19456
	s_sub_i32 s5, s5, 1
	s_cmp_lg_u32 s5, 0
	s_cbranch_scc1 .Lpipe_wo
	v_add_u32_e32 v161, s12, v160
	ds_read_b128 v[156:159], v161 offset:4096
	ds_read_b128 v[164:167], v161 offset:5120
	ds_read_b128 v[168:171], v161 offset:6144
	ds_read_b128 v[172:175], v161 offset:7168
	s_add_i32 s14, s12, 0xffffa000
	s_cmp_eq_u32 s12, 0
	s_cselect_b32 s14, 0xc000, s14
	s_add_i32 s15, s14, s13
	s_add_i32 s14, s14, s4
	s_mov_b32 m0, s15
	s_waitcnt lgkmcnt(7)
	v_mfma_f32_16x16x32_bf16 v[126:129], v[176:179], v[140:143], v[126:129]
	global_load_lds_dwordx4 v[196:197], off
	v_mfma_f32_16x16x32_bf16 v[110:113], v[176:179], v[144:147], v[110:113]
	v_lshl_add_u64 v[196:197], v[196:197], 0, s[98:99]
	s_add_i32 m0, s15, 0x400
	v_mfma_f32_16x16x32_bf16 v[94:97], v[176:179], v[148:151], v[94:97]
	global_load_lds_dwordx4 v[198:199], off
	v_mfma_f32_16x16x32_bf16 v[78:81], v[176:179], v[152:155], v[78:81]
	v_lshl_add_u64 v[198:199], v[198:199], 0, s[98:99]
	s_add_i32 m0, s15, 0x800
	s_waitcnt lgkmcnt(6)
	v_mfma_f32_16x16x32_bf16 v[122:125], v[180:183], v[140:143], v[122:125]
	global_load_lds_dwordx4 v[200:201], off
	v_mfma_f32_16x16x32_bf16 v[106:109], v[180:183], v[144:147], v[106:109]
	v_lshl_add_u64 v[200:201], v[200:201], 0, s[98:99]
	s_add_i32 m0, s15, 0xc00
	v_mfma_f32_16x16x32_bf16 v[90:93], v[180:183], v[148:151], v[90:93]
	global_load_lds_dwordx4 v[202:203], off
	v_mfma_f32_16x16x32_bf16 v[74:77], v[180:183], v[152:155], v[74:77]
	v_lshl_add_u64 v[202:203], v[202:203], 0, s[98:99]
	s_mov_b32 m0, s14
	s_waitcnt lgkmcnt(5)
; template <int MI, int NI>
; DI void gemm256(f32x4 (&acc)[MI][NI], const u16* __restrict__ A, int lda, const u16* __restrict__ Bt, int ldb, int K, int m0, int n0, char* smem) {
;     ...
;   const int nk = K >> 5;
;   G256_ISSUE(0, 0);
;   if (nk > 1) G256_ISSUE(1, 32);
;   const int foff = lr * 64 + ((lq ^ ((lr >> 3) << 1)) * 16);
;   int st = 0;
;   for (int kt = 0; kt < nk; ++kt) {
;     if (kt + 1 < nk) asm volatile("s_waitcnt vmcnt(%0) lgkmcnt(0)" :: "n"(LPS) : "memory");
;     else asm volatile("s_waitcnt vmcnt(0) lgkmcnt(0)" ::: "memory");
;     __builtin_amdgcn_s_barrier();
;     __builtin_amdgcn_s_setprio(1);
;     const char* sb = smem + st * STAGE + foff;
;     bf16x8 af[MI], bfr[NI];
; #pragma unroll
;     for (int mi = 0; mi < MI; ++mi) af[mi] = *(const bf16x8*)(sb + (wr * MI + mi) * 1024);
; #pragma unroll
;     for (int ni = 0; ni < NI; ++ni) bfr[ni] = *(const bf16x8*)(sb + ABYTES + (wc * NI + ni) * 1024);
;     __builtin_amdgcn_sched_barrier(0x0);
;     if (kt + 2 < nk) { const int s2 = st >= 1 ? st - 1 : 2; G256_ISSUE(s2, (kt + 2) * 32); }
;     __builtin_amdgcn_s_setprio(0);
; #pragma unroll
;     for (int mi = 0; mi < MI; ++mi)
; #pragma unroll
;       for (int ni = 0; ni < NI; ++ni)
;         acc[mi][ni] = __builtin_amdgcn_mfma_f32_16x16x32_bf16(bfr[ni], af[mi], acc[mi][ni], 0, 0, 0);
;     st = st == 2 ? 0 : st + 1;
;   }
;   asm volatile("s_waitcnt lgkmcnt(0)" ::: "memory");
;   __builtin_amdgcn_s_barrier();
	v_mfma_f32_16x16x32_bf16 v[118:121], v[184:187], v[140:143], v[118:121]
	global_load_lds_dwordx4 v[204:205], off
	v_mfma_f32_16x16x32_bf16 v[102:105], v[184:187], v[144:147], v[102:105]
	v_lshl_add_u64 v[204:205], v[204:205], 0, 64
	s_add_i32 m0, s14, 0x400
	v_mfma_f32_16x16x32_bf16 v[86:89], v[184:187], v[148:151], v[86:89]
	global_load_lds_dwordx4 v[206:207], off
	v_mfma_f32_16x16x32_bf16 v[70:73], v[184:187], v[152:155], v[70:73]
	v_lshl_add_u64 v[206:207], v[206:207], 0, 64
	s_waitcnt lgkmcnt(4)
	v_mfma_f32_16x16x32_bf16 v[114:117], v[188:191], v[140:143], v[114:117]
	v_mfma_f32_16x16x32_bf16 v[98:101], v[188:191], v[144:147], v[98:101]
	v_mfma_f32_16x16x32_bf16 v[82:85], v[188:191], v[148:151], v[82:85]
	v_mfma_f32_16x16x32_bf16 v[66:69], v[188:191], v[152:155], v[66:69]
	s_waitcnt lgkmcnt(0)
	v_mfma_f32_16x16x32_bf16 v[62:65], v[176:179], v[156:159], v[62:65]
	v_mfma_f32_16x16x32_bf16 v[46:49], v[176:179], v[164:167], v[46:49]
	v_mfma_f32_16x16x32_bf16 v[30:33], v[176:179], v[168:171], v[30:33]
	v_mfma_f32_16x16x32_bf16 v[14:17], v[176:179], v[172:175], v[14:17]
	v_mfma_f32_16x16x32_bf16 v[58:61], v[180:183], v[156:159], v[58:61]
	v_mfma_f32_16x16x32_bf16 v[42:45], v[180:183], v[164:167], v[42:45]
	v_mfma_f32_16x16x32_bf16 v[26:29], v[180:183], v[168:171], v[26:29]
	v_mfma_f32_16x16x32_bf16 v[10:13], v[180:183], v[172:175], v[10:13]
	v_mfma_f32_16x16x32_bf16 v[54:57], v[184:187], v[156:159], v[54:57]
	v_mfma_f32_16x16x32_bf16 v[38:41], v[184:187], v[164:167], v[38:41]
	v_mfma_f32_16x16x32_bf16 v[22:25], v[184:187], v[168:171], v[22:25]
	v_mfma_f32_16x16x32_bf16 v[6:9], v[184:187], v[172:175], v[6:9]
	v_mfma_f32_16x16x32_bf16 v[50:53], v[188:191], v[156:159], v[50:53]
	v_mfma_f32_16x16x32_bf16 v[34:37], v[188:191], v[164:167], v[34:37]
	v_mfma_f32_16x16x32_bf16 v[18:21], v[188:191], v[168:171], v[18:21]
	v_mfma_f32_16x16x32_bf16 v[2:5], v[188:191], v[172:175], v[2:5]
	s_waitcnt vmcnt(6) lgkmcnt(0)
	s_barrier
	s_setprio 1
	v_add_u32_e32 v0, v137, v139
	ds_read_b128 v[130:133], v0
	ds_read_b128 v[140:143], v0 offset:1024
	ds_read_b128 v[144:147], v0 offset:2048
	ds_read_b128 v[148:151], v0 offset:3072
	ds_read_b128 v[152:155], v0 offset:4096
	ds_read_b128 v[156:159], v0 offset:5120
	ds_read_b128 v[164:167], v0 offset:6144
	ds_read_b128 v[168:171], v0 offset:7168
	v_add_u32_e32 v184, v137, v138
	ds_read_b128 v[136:139], v184 offset:16384
	ds_read_b128 v[172:175], v184 offset:17408
	ds_read_b128 v[176:179], v184 offset:18432
	ds_read_b128 v[180:183], v184 offset:19456
	v_bfe_u32 v188, v134, 6, 1
	s_setprio 0
	s_waitcnt vmcnt(0) lgkmcnt(0)
	s_waitcnt lgkmcnt(3)
	v_mfma_f32_16x16x32_bf16 v[126:129], v[136:139], v[130:133], v[126:129]
	v_ashrrev_i32_e32 v189, 7, v134
	v_and_b32_e32 v190, 15, v134
	v_bfe_u32 v191, v134, 4, 2
	s_waitcnt lgkmcnt(2)
	v_mfma_f32_16x16x32_bf16 v[122:125], v[172:175], v[130:133], v[122:125]
	s_barrier
	s_waitcnt lgkmcnt(1)
	v_mfma_f32_16x16x32_bf16 v[118:121], v[176:179], v[130:133], v[118:121]
	s_waitcnt lgkmcnt(0)
	v_mfma_f32_16x16x32_bf16 v[114:117], v[180:183], v[130:133], v[114:117]
	v_mfma_f32_16x16x32_bf16 v[110:113], v[136:139], v[140:143], v[110:113]
	v_mfma_f32_16x16x32_bf16 v[106:109], v[172:175], v[140:143], v[106:109]
	v_mfma_f32_16x16x32_bf16 v[102:105], v[176:179], v[140:143], v[102:105]
	v_mfma_f32_16x16x32_bf16 v[98:101], v[180:183], v[140:143], v[98:101]
	v_mfma_f32_16x16x32_bf16 v[94:97], v[136:139], v[144:147], v[94:97]
	v_mfma_f32_16x16x32_bf16 v[90:93], v[172:175], v[144:147], v[90:93]
	v_mfma_f32_16x16x32_bf16 v[86:89], v[176:179], v[144:147], v[86:89]
	v_mfma_f32_16x16x32_bf16 v[82:85], v[180:183], v[144:147], v[82:85]
	v_mfma_f32_16x16x32_bf16 v[78:81], v[136:139], v[148:151], v[78:81]
	v_mfma_f32_16x16x32_bf16 v[130:133], v[172:175], v[148:151], v[74:77]
	v_mfma_f32_16x16x32_bf16 v[70:73], v[176:179], v[148:151], v[70:73]
	v_mfma_f32_16x16x32_bf16 v[66:69], v[180:183], v[148:151], v[66:69]
	v_mfma_f32_16x16x32_bf16 v[62:65], v[136:139], v[152:155], v[62:65]
	v_mfma_f32_16x16x32_bf16 v[58:61], v[172:175], v[152:155], v[58:61]
	v_mfma_f32_16x16x32_bf16 v[54:57], v[176:179], v[152:155], v[54:57]
	v_mfma_f32_16x16x32_bf16 v[50:53], v[180:183], v[152:155], v[50:53]
	v_mfma_f32_16x16x32_bf16 v[46:49], v[136:139], v[156:159], v[46:49]
	v_mfma_f32_16x16x32_bf16 v[42:45], v[172:175], v[156:159], v[42:45]
	v_mfma_f32_16x16x32_bf16 v[38:41], v[176:179], v[156:159], v[38:41]
	v_mfma_f32_16x16x32_bf16 v[34:37], v[180:183], v[156:159], v[34:37]
	v_mfma_f32_16x16x32_bf16 v[30:33], v[136:139], v[164:167], v[30:33]
	v_mfma_f32_16x16x32_bf16 v[26:29], v[172:175], v[164:167], v[26:29]
	v_mfma_f32_16x16x32_bf16 v[22:25], v[176:179], v[164:167], v[22:25]
	v_mfma_f32_16x16x32_bf16 v[18:21], v[180:183], v[164:167], v[18:21]
	v_mfma_f32_16x16x32_bf16 v[14:17], v[136:139], v[168:171], v[14:17]
	v_mfma_f32_16x16x32_bf16 v[10:13], v[172:175], v[168:171], v[10:13]
	v_mfma_f32_16x16x32_bf16 v[6:9], v[176:179], v[168:171], v[6:9]
	v_mfma_f32_16x16x32_bf16 v[134:137], v[180:183], v[168:171], v[2:5]
	s_setprio 1
	s_nop 1
	ds_read_b128 v[2:5], v0 offset:24576
	ds_read_b128 v[74:77], v0 offset:25600
	ds_read_b128 v[138:141], v0 offset:26624
	ds_read_b128 v[142:145], v0 offset:27648
	ds_read_b128 v[146:149], v0 offset:28672
	ds_read_b128 v[150:153], v0 offset:29696
	ds_read_b128 v[154:157], v0 offset:30720
	ds_read_b128 v[158:161], v0 offset:31744
	ds_read_b128 v[164:167], v184 offset:40960
	ds_read_b128 v[168:171], v184 offset:41984
	ds_read_b128 v[172:175], v184 offset:43008
	ds_read_b128 v[176:179], v184 offset:44032
	s_setprio 0
	s_waitcnt lgkmcnt(0)
	s_barrier
; template <int MI, int NI>
; DI void gemm256(f32x4 (&acc)[MI][NI], const u16* __restrict__ A, int lda, const u16* __restrict__ Bt, int ldb, int K, int m0, int n0, char* smem) {
;     ...
; #pragma unroll
;     for (int mi = 0; mi < MI; ++mi)
; #pragma unroll
;       for (int ni = 0; ni < NI; ++ni)
;         acc[mi][ni] = __builtin_amdgcn_mfma_f32_16x16x32_bf16(bfr[ni], af[mi], acc[mi][ni], 0, 0, 0);
;     st = st == 2 ? 0 : st + 1;
;   }
; template <int MI, int NI>
; DI void resid_tile(const u16* A, int K, const u16* Bt, const float* gate, const float* xl_in, const float* xc_in, float* xl_out, float* xc_out,
;                    int m0, int n0, char* smem) {
;     ...
; #pragma unroll
;   for (int mi = 0; mi < MI; ++mi) {
;     const int m = m0 + wr * 16 * MI + mi * 16 + lr;
;     const int b9 = m < NTL ? m >> 12 : 8;
;     const float* xi = xrow(xl_in, xc_in, m);
;     float* xo = m < NTL ? xl_out + (size_t)m * D : xc_out + (size_t)(m - NTL) * D;
; #pragma unroll
;     for (int ni = 0; ni < NI; ++ni) {
;       const int n = n0 + wc * 16 * NI + ni * 16 + lq * 4;
;       const float4 g = *(const float4*)(gate + (size_t)b9 * 6144 + n);
;       const float4 xv = *(const float4*)(xi + n);
;       float4 ov;
;       ov.x = xv.x + g.x * acc[mi][ni][0]; ov.y = xv.y + g.y * acc[mi][ni][1]; ov.z = xv.z + g.z * acc[mi][ni][2]; ov.w = xv.w + g.w * acc[mi][ni][3];
;       *(float4*)(xo + n) = ov;
;     }
;     __builtin_amdgcn_sched_barrier(0);
;   }
	v_readlane_b32 s4, v253, 55
	v_lshlrev_b32_e32 v0, 7, v189
	s_waitcnt lgkmcnt(3)
	v_mfma_f32_16x16x32_bf16 v[126:129], v[164:167], v[2:5], v[126:129]
	s_waitcnt lgkmcnt(2)
	v_mfma_f32_16x16x32_bf16 v[122:125], v[168:171], v[2:5], v[122:125]
	s_waitcnt lgkmcnt(1)
	v_mfma_f32_16x16x32_bf16 v[180:183], v[172:175], v[2:5], v[118:121]
	s_waitcnt lgkmcnt(0)
	v_mfma_f32_16x16x32_bf16 v[184:187], v[176:179], v[2:5], v[114:117]
	v_lshlrev_b32_e32 v2, 2, v191
	v_mov_b32_e32 v118, s4
	v_readlane_b32 s4, v253, 53
	v_add3_u32 v116, v190, s10, v0
	v_lshlrev_b32_e32 v0, 6, v188
	v_add3_u32 v2, v2, s11, v0
	v_min_i32_e32 v0, 0x8000, v116
	v_mov_b32_e32 v119, s4
	v_readlane_b32 s4, v253, 56
	v_mfma_f32_16x16x32_bf16 v[110:113], v[164:167], v[74:77], v[110:113]
	v_ashrrev_i32_e32 v117, 31, v116
	v_cmp_gt_i32_e32 vcc, s58, v116
	v_mov_b32_e32 v120, s4
	v_mfma_f32_16x16x32_bf16 v[106:109], v[168:171], v[74:77], v[106:109]
	v_readlane_b32 s4, v253, 54
	v_cndmask_b32_e32 v5, 0, v117, vcc
	v_cndmask_b32_e32 v115, v118, v119, vcc
	v_mfma_f32_16x16x32_bf16 v[102:105], v[172:175], v[74:77], v[102:105]
	v_mov_b32_e32 v121, s4
	v_cndmask_b32_e32 v114, v120, v121, vcc
	v_readlane_b32 s4, v253, 51
	v_mfma_f32_16x16x32_bf16 v[98:101], v[176:179], v[74:77], v[98:101]
	v_ashrrev_i32_e32 v3, 31, v2
	v_readlane_b32 s5, v253, 52
	v_mfma_f32_16x16x32_bf16 v[74:77], v[164:167], v[142:145], v[78:81]
	v_mfma_f32_16x16x32_bf16 v[78:81], v[168:171], v[142:145], v[130:133]
	s_nop 2
	v_ashrrev_i32_e32 v130, 12, v0
	v_add_u32_e32 v0, 0xffff8000, v116
	v_cndmask_b32_e32 v4, v0, v116, vcc
	v_lshlrev_b64 v[4:5], 12, v[4:5]
	v_lshl_add_u64 v[4:5], v[114:115], 0, v[4:5]
	v_mul_hi_i32_i24_e32 v115, 0x6000, v130
	v_mul_i32_i24_e32 v114, 0x6000, v130
	v_lshl_add_u64 v[130:131], s[4:5], 0, v[114:115]
	v_lshlrev_b64 v[114:115], 2, v[2:3]
	v_mfma_f32_16x16x32_bf16 v[94:97], v[164:167], v[138:141], v[94:97]
	v_mfma_f32_16x16x32_bf16 v[90:93], v[168:171], v[138:141], v[90:93]
	v_mfma_f32_16x16x32_bf16 v[86:89], v[172:175], v[138:141], v[86:89]
	v_mfma_f32_16x16x32_bf16 v[82:85], v[176:179], v[138:141], v[82:85]
	v_lshl_add_u64 v[138:139], v[130:131], 0, v[114:115]
	v_lshl_add_u64 v[140:141], v[4:5], 0, v[114:115]
	flat_load_dwordx4 v[2:5], v[138:139]
	flat_load_dwordx4 v[130:133], v[140:141]
	v_mfma_f32_16x16x32_bf16 v[70:73], v[172:175], v[142:145], v[70:73]
	s_waitcnt vmcnt(0) lgkmcnt(0)
	v_pk_fma_f32 v[2:3], v[126:127], v[2:3], v[130:131]
	v_mfma_f32_16x16x32_bf16 v[66:69], v[176:179], v[142:145], v[66:69]
	v_lshlrev_b64 v[142:143], 12, v[116:117]
	v_lshlrev_b64 v[144:145], 12, v[0:1]
	v_lshl_add_u64 v[142:143], s[48:49], 0, v[142:143]
	v_lshl_add_u64 v[144:145], s[94:95], 0, v[144:145]
	v_cndmask_b32_e32 v143, v145, v143, vcc
	v_cndmask_b32_e32 v142, v144, v142, vcc
	v_lshl_add_u64 v[142:143], v[142:143], 0, v[114:115]
	v_pk_fma_f32 v[4:5], v[128:129], v[4:5], v[132:133]
	flat_store_dwordx4 v[142:143], v[2:5]
	flat_load_dwordx4 v[126:129], v[138:139] offset:64
	flat_load_dwordx4 v[130:133], v[140:141] offset:64
	v_mfma_f32_16x16x32_bf16 v[2:5], v[168:171], v[158:161], v[10:13]
	v_mfma_f32_16x16x32_bf16 v[62:65], v[164:167], v[146:149], v[62:65]
	s_waitcnt vmcnt(0) lgkmcnt(0)
	s_nop 0
	v_pk_fma_f32 v[10:11], v[122:123], v[126:127], v[130:131]
	v_pk_fma_f32 v[12:13], v[124:125], v[128:129], v[132:133]
	flat_store_dwordx4 v[142:143], v[10:13] offset:64
	flat_load_dwordx4 v[10:13], v[138:139] offset:128
	s_nop 0
	flat_load_dwordx4 v[122:125], v[140:141] offset:128
	v_mfma_f32_16x16x32_bf16 v[58:61], v[168:171], v[146:149], v[58:61]
	s_waitcnt vmcnt(0) lgkmcnt(0)
	v_pk_fma_f32 v[10:11], v[180:181], v[10:11], v[122:123]
	v_pk_fma_f32 v[12:13], v[182:183], v[12:13], v[124:125]
	flat_store_dwordx4 v[142:143], v[10:13] offset:128
	flat_load_dwordx4 v[122:125], v[138:139] offset:192
	flat_load_dwordx4 v[126:129], v[140:141] offset:192
	v_mfma_f32_16x16x32_bf16 v[54:57], v[172:175], v[146:149], v[54:57]
	s_waitcnt vmcnt(0) lgkmcnt(0)
	v_pk_fma_f32 v[122:123], v[184:185], v[122:123], v[126:127]
	v_pk_fma_f32 v[124:125], v[186:187], v[124:125], v[128:129]
	v_mfma_f32_16x16x32_bf16 v[50:53], v[176:179], v[146:149], v[50:53]
	flat_store_dwordx4 v[142:143], v[122:125] offset:192
	v_mfma_f32_16x16x32_bf16 v[46:49], v[164:167], v[150:153], v[46:49]
	v_mfma_f32_16x16x32_bf16 v[42:45], v[168:171], v[150:153], v[42:45]
	v_mfma_f32_16x16x32_bf16 v[38:41], v[172:175], v[150:153], v[38:41]
	v_mfma_f32_16x16x32_bf16 v[34:37], v[176:179], v[150:153], v[34:37]
	v_mfma_f32_16x16x32_bf16 v[30:33], v[164:167], v[154:157], v[30:33]
	v_mfma_f32_16x16x32_bf16 v[26:29], v[168:171], v[154:157], v[26:29]
	v_mfma_f32_16x16x32_bf16 v[22:25], v[172:175], v[154:157], v[22:25]
	v_mfma_f32_16x16x32_bf16 v[18:21], v[176:179], v[154:157], v[18:21]
	v_mfma_f32_16x16x32_bf16 v[14:17], v[164:167], v[158:161], v[14:17]
	v_mfma_f32_16x16x32_bf16 v[6:9], v[172:175], v[158:161], v[6:9]
	v_mfma_f32_16x16x32_bf16 v[10:13], v[176:179], v[158:161], v[134:137]
	v_add_u32_e32 v122, 16, v116
	v_min_i32_e32 v0, 0x8000, v122
	v_cmp_gt_i32_e32 vcc, s58, v122
	v_ashrrev_i32_e32 v117, 12, v0
	v_add_u32_e32 v0, 0xffff8010, v116
	v_ashrrev_i32_e32 v123, 31, v122
	v_cndmask_b32_e32 v125, 0, v123, vcc
	v_cndmask_b32_e32 v124, v0, v122, vcc
	v_cndmask_b32_e32 v127, v118, v119, vcc
	v_cndmask_b32_e32 v126, v120, v121, vcc
	v_lshlrev_b64 v[124:125], 12, v[124:125]
	v_lshl_add_u64 v[124:125], v[126:127], 0, v[124:125]
	v_lshlrev_b64 v[122:123], 12, v[122:123]
	v_lshlrev_b64 v[126:127], 12, v[0:1]
	v_lshl_add_u64 v[122:123], s[48:49], 0, v[122:123]
	v_lshl_add_u64 v[126:127], s[94:95], 0, v[126:127]
	v_cndmask_b32_e32 v123, v127, v123, vcc
	v_cndmask_b32_e32 v122, v126, v122, vcc
	v_mul_hi_i32_i24_e32 v127, 0x6000, v117
	v_mul_i32_i24_e32 v126, 0x6000, v117
	v_lshl_add_u64 v[126:127], s[4:5], 0, v[126:127]
	v_lshl_add_u64 v[130:131], v[126:127], 0, v[114:115]
	v_lshl_add_u64 v[132:133], v[124:125], 0, v[114:115]
	v_lshl_add_u64 v[134:135], v[122:123], 0, v[114:115]
	global_load_dwordx4 v[156:159], v[130:131], off
	global_load_dwordx4 v[164:167], v[130:131], off offset:64
	global_load_dwordx4 v[168:171], v[130:131], off offset:128
	global_load_dwordx4 v[172:175], v[130:131], off offset:192
	global_load_dwordx4 v[140:143], v[132:133], off
	global_load_dwordx4 v[144:147], v[132:133], off offset:64
	global_load_dwordx4 v[148:151], v[132:133], off offset:128
	global_load_dwordx4 v[152:155], v[132:133], off offset:192
	v_mov_b32_e32 v216, 0x10000
	v_mov_b32_e32 v217, 0
	v_lshl_add_u64 v[212:213], v[132:133], 0, v[216:217]
	v_lshl_add_u64 v[214:215], v[134:135], 0, v[216:217]
	global_load_dwordx4 v[176:179], v[212:213], off
	global_load_dwordx4 v[180:183], v[212:213], off offset:64
	global_load_dwordx4 v[184:187], v[212:213], off offset:128
	global_load_dwordx4 v[188:191], v[212:213], off offset:192
	v_lshl_add_u64 v[212:213], v[212:213], 0, v[216:217]
	s_waitcnt vmcnt(4)
; template <int MI, int NI>
; DI void resid_tile(const u16* A, int K, const u16* Bt, const float* gate, const float* xl_in, const float* xc_in, float* xl_out, float* xc_out,
;                    int m0, int n0, char* smem) {
;     ...
; #pragma unroll
;   for (int mi = 0; mi < MI; ++mi) {
;     const int m = m0 + wr * 16 * MI + mi * 16 + lr;
;     const int b9 = m < NTL ? m >> 12 : 8;
;     const float* xi = xrow(xl_in, xc_in, m);
;     float* xo = m < NTL ? xl_out + (size_t)m * D : xc_out + (size_t)(m - NTL) * D;
; #pragma unroll
;     for (int ni = 0; ni < NI; ++ni) {
;       const int n = n0 + wc * 16 * NI + ni * 16 + lq * 4;
;       const float4 g = *(const float4*)(gate + (size_t)b9 * 6144 + n);
;       const float4 xv = *(const float4*)(xi + n);
;       float4 ov;
;       ov.x = xv.x + g.x * acc[mi][ni][0]; ov.y = xv.y + g.y * acc[mi][ni][1]; ov.z = xv.z + g.z * acc[mi][ni][2]; ov.w = xv.w + g.w * acc[mi][ni][3];
;       *(float4*)(xo + n) = ov;
;     }
;     __builtin_amdgcn_sched_barrier(0);
;   }
	v_pk_fma_f32 v[110:111], v[110:111], v[156:157], v[140:141]
	v_pk_fma_f32 v[112:113], v[112:113], v[158:159], v[142:143]
	v_pk_fma_f32 v[106:107], v[106:107], v[164:165], v[144:145]
	v_pk_fma_f32 v[108:109], v[108:109], v[166:167], v[146:147]
	v_pk_fma_f32 v[102:103], v[102:103], v[168:169], v[148:149]
	v_pk_fma_f32 v[104:105], v[104:105], v[170:171], v[150:151]
	v_pk_fma_f32 v[98:99], v[98:99], v[172:173], v[152:153]
	v_pk_fma_f32 v[100:101], v[100:101], v[174:175], v[154:155]
	global_store_dwordx4 v[134:135], v[110:113], off
	global_store_dwordx4 v[134:135], v[106:109], off offset:64
	global_store_dwordx4 v[134:135], v[102:105], off offset:128
	global_store_dwordx4 v[134:135], v[98:101], off offset:192
	global_load_dwordx4 v[140:143], v[212:213], off
	global_load_dwordx4 v[144:147], v[212:213], off offset:64
	global_load_dwordx4 v[148:151], v[212:213], off offset:128
	global_load_dwordx4 v[152:155], v[212:213], off offset:192
	v_lshl_add_u64 v[212:213], v[212:213], 0, v[216:217]
	s_waitcnt vmcnt(8)
	v_pk_fma_f32 v[94:95], v[94:95], v[156:157], v[176:177]
	v_pk_fma_f32 v[96:97], v[96:97], v[158:159], v[178:179]
	v_pk_fma_f32 v[90:91], v[90:91], v[164:165], v[180:181]
	v_pk_fma_f32 v[92:93], v[92:93], v[166:167], v[182:183]
	v_pk_fma_f32 v[86:87], v[86:87], v[168:169], v[184:185]
	v_pk_fma_f32 v[88:89], v[88:89], v[170:171], v[186:187]
	v_pk_fma_f32 v[82:83], v[82:83], v[172:173], v[188:189]
	v_pk_fma_f32 v[84:85], v[84:85], v[174:175], v[190:191]
	global_store_dwordx4 v[214:215], v[94:97], off
	global_store_dwordx4 v[214:215], v[90:93], off offset:64
	global_store_dwordx4 v[214:215], v[86:89], off offset:128
	global_store_dwordx4 v[214:215], v[82:85], off offset:192
	v_lshl_add_u64 v[214:215], v[214:215], 0, v[216:217]
	global_load_dwordx4 v[176:179], v[212:213], off
	global_load_dwordx4 v[180:183], v[212:213], off offset:64
	global_load_dwordx4 v[184:187], v[212:213], off offset:128
	global_load_dwordx4 v[188:191], v[212:213], off offset:192
	v_lshl_add_u64 v[212:213], v[212:213], 0, v[216:217]
	s_waitcnt vmcnt(8)
	v_pk_fma_f32 v[74:75], v[74:75], v[156:157], v[140:141]
	v_pk_fma_f32 v[76:77], v[76:77], v[158:159], v[142:143]
	v_pk_fma_f32 v[78:79], v[78:79], v[164:165], v[144:145]
	v_pk_fma_f32 v[80:81], v[80:81], v[166:167], v[146:147]
	v_pk_fma_f32 v[70:71], v[70:71], v[168:169], v[148:149]
	v_pk_fma_f32 v[72:73], v[72:73], v[170:171], v[150:151]
	v_pk_fma_f32 v[66:67], v[66:67], v[172:173], v[152:153]
	v_pk_fma_f32 v[68:69], v[68:69], v[174:175], v[154:155]
	global_store_dwordx4 v[214:215], v[74:77], off
	global_store_dwordx4 v[214:215], v[78:81], off offset:64
	global_store_dwordx4 v[214:215], v[70:73], off offset:128
	global_store_dwordx4 v[214:215], v[66:69], off offset:192
	v_lshl_add_u64 v[214:215], v[214:215], 0, v[216:217]
	global_load_dwordx4 v[140:143], v[212:213], off
	global_load_dwordx4 v[144:147], v[212:213], off offset:64
	global_load_dwordx4 v[148:151], v[212:213], off offset:128
	global_load_dwordx4 v[152:155], v[212:213], off offset:192
	v_lshl_add_u64 v[212:213], v[212:213], 0, v[216:217]
	s_waitcnt vmcnt(8)
	v_pk_fma_f32 v[62:63], v[62:63], v[156:157], v[176:177]
	v_pk_fma_f32 v[64:65], v[64:65], v[158:159], v[178:179]
	v_pk_fma_f32 v[58:59], v[58:59], v[164:165], v[180:181]
	v_pk_fma_f32 v[60:61], v[60:61], v[166:167], v[182:183]
	v_pk_fma_f32 v[54:55], v[54:55], v[168:169], v[184:185]
	v_pk_fma_f32 v[56:57], v[56:57], v[170:171], v[186:187]
	v_pk_fma_f32 v[50:51], v[50:51], v[172:173], v[188:189]
	v_pk_fma_f32 v[52:53], v[52:53], v[174:175], v[190:191]
	global_store_dwordx4 v[214:215], v[62:65], off
	global_store_dwordx4 v[214:215], v[58:61], off offset:64
	global_store_dwordx4 v[214:215], v[54:57], off offset:128
	global_store_dwordx4 v[214:215], v[50:53], off offset:192
	v_lshl_add_u64 v[214:215], v[214:215], 0, v[216:217]
	global_load_dwordx4 v[176:179], v[212:213], off
	global_load_dwordx4 v[180:183], v[212:213], off offset:64
	global_load_dwordx4 v[184:187], v[212:213], off offset:128
	global_load_dwordx4 v[188:191], v[212:213], off offset:192
	v_lshl_add_u64 v[212:213], v[212:213], 0, v[216:217]
	s_waitcnt vmcnt(8)
	v_pk_fma_f32 v[46:47], v[46:47], v[156:157], v[140:141]
	v_pk_fma_f32 v[48:49], v[48:49], v[158:159], v[142:143]
	v_pk_fma_f32 v[42:43], v[42:43], v[164:165], v[144:145]
	v_pk_fma_f32 v[44:45], v[44:45], v[166:167], v[146:147]
	v_pk_fma_f32 v[38:39], v[38:39], v[168:169], v[148:149]
	v_pk_fma_f32 v[40:41], v[40:41], v[170:171], v[150:151]
	v_pk_fma_f32 v[34:35], v[34:35], v[172:173], v[152:153]
	v_pk_fma_f32 v[36:37], v[36:37], v[174:175], v[154:155]
	global_store_dwordx4 v[214:215], v[46:49], off
	global_store_dwordx4 v[214:215], v[42:45], off offset:64
	global_store_dwordx4 v[214:215], v[38:41], off offset:128
	global_store_dwordx4 v[214:215], v[34:37], off offset:192
	v_lshl_add_u64 v[214:215], v[214:215], 0, v[216:217]
	global_load_dwordx4 v[140:143], v[212:213], off
	global_load_dwordx4 v[144:147], v[212:213], off offset:64
	global_load_dwordx4 v[148:151], v[212:213], off offset:128
	global_load_dwordx4 v[152:155], v[212:213], off offset:192
	s_waitcnt vmcnt(8)
	v_pk_fma_f32 v[30:31], v[30:31], v[156:157], v[176:177]
	v_pk_fma_f32 v[32:33], v[32:33], v[158:159], v[178:179]
	v_pk_fma_f32 v[26:27], v[26:27], v[164:165], v[180:181]
	v_pk_fma_f32 v[28:29], v[28:29], v[166:167], v[182:183]
	v_pk_fma_f32 v[22:23], v[22:23], v[168:169], v[184:185]
	v_pk_fma_f32 v[24:25], v[24:25], v[170:171], v[186:187]
	v_pk_fma_f32 v[18:19], v[18:19], v[172:173], v[188:189]
	v_pk_fma_f32 v[20:21], v[20:21], v[174:175], v[190:191]
	global_store_dwordx4 v[214:215], v[30:33], off
	global_store_dwordx4 v[214:215], v[26:29], off offset:64
	global_store_dwordx4 v[214:215], v[22:25], off offset:128
	global_store_dwordx4 v[214:215], v[18:21], off offset:192
	v_lshl_add_u64 v[214:215], v[214:215], 0, v[216:217]
	s_waitcnt vmcnt(4)
	v_pk_fma_f32 v[14:15], v[14:15], v[156:157], v[140:141]
	v_pk_fma_f32 v[16:17], v[16:17], v[158:159], v[142:143]
	v_pk_fma_f32 v[2:3], v[2:3], v[164:165], v[144:145]
	v_pk_fma_f32 v[4:5], v[4:5], v[166:167], v[146:147]
	v_pk_fma_f32 v[6:7], v[6:7], v[168:169], v[148:149]
	v_pk_fma_f32 v[8:9], v[8:9], v[170:171], v[150:151]
	v_pk_fma_f32 v[10:11], v[10:11], v[172:173], v[152:153]
	v_pk_fma_f32 v[12:13], v[12:13], v[174:175], v[154:155]
	global_store_dwordx4 v[214:215], v[14:17], off
	global_store_dwordx4 v[214:215], v[2:5], off offset:64
	global_store_dwordx4 v[214:215], v[6:9], off offset:128
	global_store_dwordx4 v[214:215], v[10:13], off offset:192
	s_add_i32 s9, s9, 1
	s_mul_i32 s4, s9, s39
	s_add_i32 s4, s4, s7
	s_cmpk_gt_i32 s4, 0x7f
	s_cbranch_scc0 .LBB0_461

; DI void attn_item(const Params& p, int item, char* smem) {
;   LAUNDER_IDS
;   const int tid = tid__, lane = tid & 63, wave = tid >> 6, r32 = lane & 31, hi = lane >> 5;
;   int bh, qpos0, key0, nkt, orow0;
;   if (item < 2048) { bh = item >> 5; const int qb = item & 31; qpos0 = qb * 128; key0 = 0; nkt = LK / 64; orow0 = (bh >> 3) * L + qpos0; }
;   else { const int it = item - 2048; bh = it >> 1; const int qb = it & 1; qpos0 = 4096 + qb * 128; key0 = 4096; nkt = LC / 64; orow0 = NTL + (bh >> 3) * LC + qb * 128; }
;   const int h = bh & 7;
;   const u16* Qp = (const u16*)(p.ws + OFF_R1) + ((size_t)bh * LK + qpos0 + wave * 32 + r32) * 96 + hi * 8;
;   const u16* Kp = (const u16*)(p.ws + OFF_R1 + SZ_Q) + ((size_t)bh * LK + key0) * 96;
;   const u16* Vp = (const u16*)(p.ws + OFF_R1 + 2 * SZ_Q) + (size_t)bh * 64 * LK + key0;
;   u16* Ks = (u16*)smem;
;   u16* Vs = Ks + 2 * 64 * KSL;
;   bf16x8 qr[6];
; #pragma unroll
;   for (int d0 = 0; d0 < 6; ++d0) qr[d0] = *(const bf16x8*)(Qp + d0 * 16);
;   uint4 ak0, ak1, ak2, av0, av1, bk0, bk1, bk2, bv0, bv1;
;   const int kr0 = tid / 12, kc0 = tid - kr0 * 12, kr1 = (tid + 256) / 12, kc1 = (tid + 256) - kr1 * 12, kr2 = (tid + 512) / 12, kc2 = (tid + 512) - kr2 * 12;
;   const int vd0 = tid >> 3, vc0 = tid & 7, vd1 = vd0 + 32;
;     ...
;   f32x16 o0, o1;
; #pragma unroll
;   for (int i = 0; i < 16; ++i) { o0[i] = 0.f; o1[i] = 0.f; }
;   float mrun = -1e30f, lrun = 0.f;
;   auto tile_compute = [&](int cur) {
;     const u16* Kc = Ks + cur * 64 * KSL;
;     const u16* Vc = Vs + cur * 64 * VSL;
;     f32x16 p0, p1;
; #pragma unroll
;     for (int i = 0; i < 16; ++i) { p0[i] = 0.f; p1[i] = 0.f; }
; #pragma unroll
;     for (int d0 = 0; d0 < 6; ++d0) {
;       const bf16x8 a0 = *(const bf16x8*)(Kc + r32 * KSL + d0 * 16 + hi * 8);
;       const bf16x8 a1 = *(const bf16x8*)(Kc + (32 + r32) * KSL + d0 * 16 + hi * 8);
;       p0 = __builtin_amdgcn_mfma_f32_32x32x16_bf16(a0, qr[d0], p0, 0, 0, 0);
;       p1 = __builtin_amdgcn_mfma_f32_32x32x16_bf16(a1, qr[d0], p1, 0, 0, 0);
;     }
;     float mx = p0[0];
; #pragma unroll
;     for (int i = 1; i < 16; ++i) mx = fmaxf(mx, p0[i]);
; #pragma unroll
;     for (int i = 0; i < 16; ++i) mx = fmaxf(mx, p1[i]);
;     { auto rr = __builtin_amdgcn_permlane32_swap(__float_as_uint(mx), __float_as_uint(mx), false, false);
;       mx = fmaxf(__uint_as_float(rr[0]), __uint_as_float(rr[1])); }
.LBB0_528:
	v_ashrrev_i32_e32 v0, 1, v2
	v_and_b32_e32 v3, 31, v2
	v_and_b32_e32 v0, 0xffffffe0, v0
	v_ashrrev_i32_e32 v137, 31, v0
	v_or_b32_e32 v136, v0, v3
	s_waitcnt vmcnt(0)
	v_lshl_add_u64 v[4:5], v[136:137], 0, s[64:65]
	v_mov_b32_e32 v0, 0x1100
	v_mad_i64_i32 v[4:5], s[6:7], s8, v0, v[4:5]
	v_mov_b64_e32 v[6:7], s[60:61]
	v_bfe_u32 v44, v2, 5, 1
	v_mad_u64_u32 v[6:7], s[6:7], v4, s72, v[6:7]
	v_mad_i32_i24 v7, v5, s72, v7
	v_lshlrev_b32_e32 v0, 4, v44
	v_lshl_add_u64 v[4:5], v[6:7], 0, v[0:1]
	flat_load_dwordx4 v[80:83], v[4:5]
	flat_load_dwordx4 v[84:87], v[4:5] offset:32
	flat_load_dwordx4 v[88:91], v[4:5] offset:64
	flat_load_dwordx4 v[92:95], v[4:5] offset:96
	flat_load_dwordx4 v[96:99], v[4:5] offset:128
	flat_load_dwordx4 v[100:103], v[4:5] offset:160
	v_mul_hi_i32 v4, v2, s73
	s_mul_i32 s12, s8, 0x1100
	v_lshrrev_b32_e32 v5, 31, v4
	v_ashrrev_i32_e32 v4, 1, v4
	s_mul_hi_i32 s11, s8, 0x1100
	s_add_u32 s6, s12, s4
	v_add_u32_e32 v45, v4, v5
	v_add_u32_e32 v4, 0x100, v2
	s_addc_u32 s5, s11, s5
	v_mul_hi_i32 v5, v4, s73
	s_mulk_i32 s5, 0xc0
	s_mul_hi_u32 s7, s6, 0xc0
	v_lshrrev_b32_e32 v6, 31, v5
	v_ashrrev_i32_e32 v5, 1, v5
	s_add_i32 s7, s7, s5
	s_mul_i32 s11, s8, 0x88000
	v_readlane_b32 s12, v254, 15
	v_add_u32_e32 v46, v5, v6
	v_add_u32_e32 v6, 0x200, v2
	s_mul_hi_i32 s5, s8, 0x88000
	v_readlane_b32 s13, v254, 16
	s_add_u32 s11, s12, s11
	v_mul_hi_i32 v5, v6, s73
	s_mulk_i32 s6, 0xc0
	s_addc_u32 s5, s13, s5
	v_readlane_b32 s12, v254, 17
	v_lshrrev_b32_e32 v7, 31, v5
	v_ashrrev_i32_e32 v5, 1, v5
	v_readlane_b32 s13, v254, 18
	s_add_u32 s6, s12, s6
	v_add_u32_e32 v47, v5, v7
	s_addc_u32 s7, s13, s7
	s_lshl_b32 s64, s4, 1
	v_mad_u64_u32 v[24:25], s[14:15], v45, -12, v[2:3]
	v_mad_u64_u32 v[26:27], s[14:15], v46, -12, v[4:5]
	v_mad_u64_u32 v[28:29], s[14:15], v47, -12, v[6:7]
	s_add_u32 s12, s11, s64
	v_lshlrev_b32_e32 v6, 3, v24
	v_lshlrev_b32_e32 v8, 3, v26
	v_lshlrev_b32_e32 v14, 3, v28
	v_ashrrev_i32_e32 v48, 3, v2
	s_addc_u32 s13, s5, 0
	v_mov_b64_e32 v[30:31], s[6:7]
	v_ashrrev_i32_e32 v7, 31, v6
	v_ashrrev_i32_e32 v9, 31, v8
	v_ashrrev_i32_e32 v15, 31, v14
	v_add_u32_e32 v18, 32, v48
	v_mad_i64_i32 v[4:5], s[6:7], v45, s72, v[30:31]
	v_lshlrev_b64 v[32:33], 1, v[6:7]
	v_mad_i64_i32 v[6:7], s[6:7], v46, s72, v[30:31]
	v_lshlrev_b64 v[34:35], 1, v[8:9]
	v_mad_i64_i32 v[12:13], s[6:7], v47, s72, v[30:31]
	v_lshlrev_b64 v[36:37], 1, v[14:15]
	v_mov_b64_e32 v[14:15], s[12:13]
	s_movk_i32 s11, 0x2200
	v_lshlrev_b32_e32 v19, 4, v2
	v_lshl_add_u64 v[4:5], v[4:5], 0, v[32:33]
	v_lshl_add_u64 v[8:9], v[6:7], 0, v[34:35]
	v_lshl_add_u64 v[12:13], v[12:13], 0, v[36:37]
	v_mad_i64_i32 v[16:17], s[6:7], v48, s11, v[14:15]
	v_and_b32_e32 v38, 0x70, v19
	v_mov_b32_e32 v39, v1
	v_mad_i64_i32 v[14:15], s[6:7], v18, s11, v[14:15]
	s_waitcnt lgkmcnt(0)
	s_barrier
	flat_load_dwordx4 v[4:7], v[4:5]
	s_nop 0
	flat_load_dwordx4 v[8:11], v[8:9]
	v_lshl_add_u64 v[40:41], v[16:17], 0, v[38:39]
	v_lshl_add_u64 v[42:43], v[14:15], 0, v[38:39]
	flat_load_dwordx4 v[12:15], v[12:13]
	s_nop 0
	flat_load_dwordx4 v[16:19], v[40:41]
	flat_load_dwordx4 v[20:23], v[42:43]
	s_movk_i32 s5, 0xd0
	v_mul_lo_u32 v25, v45, s5
	v_lshl_add_u32 v150, v24, 4, v25
	v_mul_lo_u32 v24, v46, s5
	v_lshl_add_u32 v151, v26, 4, v24
	v_mul_lo_u32 v24, v47, s5
	s_movk_i32 s5, 0x88
	v_mad_u64_u32 v[138:139], s[6:7], v48, s5, v[38:39]
	v_lshl_add_u32 v152, v28, 4, v24
	v_add_u32_e32 v139, 0x6800, v138
	v_add_u32_e32 v24, 0x7900, v138
	s_waitcnt vmcnt(0) lgkmcnt(0)
	ds_write_b128 v150, v[4:7]
	ds_write_b128 v151, v[8:11]
	ds_write_b128 v152, v[12:15]
	ds_write2_b64 v139, v[16:17], v[18:19] offset1:1
	ds_write2_b64 v24, v[20:21], v[22:23] offset1:1
	v_add_u32_e32 v4, 64, v45
	v_mad_i64_i32 v[4:5], s[6:7], v4, s72, v[30:31]
	v_add_u32_e32 v6, 64, v46
	v_lshl_add_u64 v[4:5], v[4:5], 0, v[32:33]
	v_mad_i64_i32 v[6:7], s[6:7], v6, s72, v[30:31]
	v_lshl_add_u64 v[6:7], v[6:7], 0, v[34:35]
	flat_load_dwordx4 v[104:107], v[4:5]
	flat_load_dwordx4 v[108:111], v[6:7]
	v_add_u32_e32 v4, 64, v47
	v_mad_i64_i32 v[4:5], s[6:7], v4, s72, v[30:31]
	v_lshl_add_u64 v[4:5], v[4:5], 0, v[36:37]
	flat_load_dwordx4 v[112:115], v[4:5]
	flat_load_dwordx4 v[116:119], v[40:41] offset:128
	flat_load_dwordx4 v[120:123], v[42:43] offset:128
	v_mul_u32_u24_e32 v7, 0x68, v3
	v_lshlrev_b32_e32 v7, 1, v7
	v_lshlrev_b32_e32 v6, 3, v44
	v_add_u32_e32 v154, v7, v0
	v_mul_i32_i24_e32 v0, 0xffffffb8, v3
	v_mad_i64_i32 v[4:5], s[6:7], v48, s11, 0
	v_add3_u32 v155, v7, v0, v6
	v_mov_b32_e32 v0, 0x88000
	v_mad_i64_i32 v[4:5], s[6:7], s8, v0, v[4:5]
	s_mul_i32 s6, s8, 0xcc000
	s_mulk_i32 s4, 0xc0
	s_mul_hi_i32 s5, s8, 0xcc000
	s_add_u32 s4, s6, s4
	v_and_b32_e32 v0, 7, v2
	s_addc_u32 s5, s5, 0
	v_lshl_or_b32 v4, v0, 4, v4
	v_mov_b64_e32 v[2:3], s[4:5]
	v_lshl_add_u64 v[140:141], v[4:5], 0, s[64:65]
	v_mad_i64_i32 v[4:5], s[4:5], v47, s72, v[2:3]
	v_lshl_add_u64 v[142:143], v[4:5], 0, v[36:37]
	v_mad_i64_i32 v[4:5], s[4:5], v46, s72, v[2:3]
	v_mad_i64_i32 v[2:3], s[4:5], v45, s72, v[2:3]
	v_mov_b32_e32 v14, v1
	v_mov_b32_e32 v15, v1
	v_lshlrev_b32_e32 v137, 2, v44
	v_lshl_add_u64 v[144:145], v[4:5], 0, v[34:35]
	v_lshl_add_u64 v[146:147], v[2:3], 0, v[32:33]
	v_mov_b32_e32 v0, v1
	v_mov_b32_e32 v2, v1
	v_mov_b32_e32 v3, v1
	v_mov_b32_e32 v4, v1
	v_mov_b32_e32 v5, v1
	v_mov_b32_e32 v6, v1
	v_mov_b32_e32 v7, v1
	v_mov_b32_e32 v8, v1
	v_mov_b32_e32 v9, v1
	v_mov_b32_e32 v10, v1
	v_mov_b32_e32 v11, v1
	v_mov_b32_e32 v12, v1
	v_mov_b32_e32 v13, v1
	v_mov_b64_e32 v[30:31], v[14:15]
	v_mov_b64_e32 v[46:47], v[14:15]
	v_add_u32_e32 v153, 0x1100, v138
	v_add_u32_e32 v224, 0x7800, v155
	v_add_u32_e32 v225, 0x6800, v155
	v_add_u32_e32 v226, 0x8a00, v138
	v_add_u32_e32 v227, 0x8a00, v153
	v_add_u32_e32 v228, 0x8800, v155
	v_add_u32_e32 v229, 0x9800, v155
	v_add_u32_e32 v230, 0x6800, v153
	s_mov_b32 s12, 0
	v_mov_b32_e32 v156, 0xf149f2ca
	v_mov_b32_e32 v196, 0
	v_mov_b32_e32 v197, 0
	v_mov_b32_e32 v198, 0
	v_mov_b32_e32 v199, 0
	v_mov_b32_e32 v200, 0
	v_mov_b32_e32 v201, 0
	v_mov_b32_e32 v202, 0
	v_mov_b32_e32 v203, 0
	v_mov_b32_e32 v204, 0
	v_mov_b32_e32 v205, 0
	v_mov_b32_e32 v206, 0
	v_mov_b32_e32 v207, 0
	v_mov_b32_e32 v208, 0
	v_mov_b32_e32 v209, 0
	v_mov_b32_e32 v210, 0
	v_mov_b32_e32 v211, 0
	s_mov_b32 s98, 0xff800000
	s_mov_b32 s99, 0xff800000
	v_mov_b32_e32 v157, 0
	v_mov_b64_e32 v[28:29], v[12:13]
	v_mov_b64_e32 v[26:27], v[10:11]
	v_mov_b64_e32 v[24:25], v[8:9]
	v_mov_b64_e32 v[22:23], v[6:7]
	v_mov_b64_e32 v[20:21], v[4:5]
	v_mov_b64_e32 v[18:19], v[2:3]
	v_mov_b64_e32 v[16:17], v[0:1]
	v_mov_b64_e32 v[44:45], v[12:13]
	v_mov_b64_e32 v[42:43], v[10:11]
	v_mov_b64_e32 v[40:41], v[8:9]
	v_mov_b64_e32 v[38:39], v[6:7]
	v_mov_b64_e32 v[36:37], v[4:5]
	v_mov_b64_e32 v[34:35], v[2:3]
	v_mov_b64_e32 v[32:33], v[0:1]
	s_waitcnt lgkmcnt(0)
	s_barrier

; DI void attn_item(const Params& p, int item, char* smem) {
;     ...
;   auto tile_compute = [&](int cur) {
;     const u16* Kc = Ks + cur * 64 * KSL;
;     const u16* Vc = Vs + cur * 64 * VSL;
;     f32x16 p0, p1;
; #pragma unroll
;     for (int i = 0; i < 16; ++i) { p0[i] = 0.f; p1[i] = 0.f; }
; #pragma unroll
;     for (int d0 = 0; d0 < 6; ++d0) {
;       const bf16x8 a0 = *(const bf16x8*)(Kc + r32 * KSL + d0 * 16 + hi * 8);
;       const bf16x8 a1 = *(const bf16x8*)(Kc + (32 + r32) * KSL + d0 * 16 + hi * 8);
;       p0 = __builtin_amdgcn_mfma_f32_32x32x16_bf16(a0, qr[d0], p0, 0, 0, 0);
;       p1 = __builtin_amdgcn_mfma_f32_32x32x16_bf16(a1, qr[d0], p1, 0, 0, 0);
;     }
;     float mx = p0[0];
; #pragma unroll
;     for (int i = 1; i < 16; ++i) mx = fmaxf(mx, p0[i]);
; #pragma unroll
;     for (int i = 0; i < 16; ++i) mx = fmaxf(mx, p1[i]);
;     { auto rr = __builtin_amdgcn_permlane32_swap(__float_as_uint(mx), __float_as_uint(mx), false, false);
;       mx = fmaxf(__uint_as_float(rr[0]), __uint_as_float(rr[1])); }
;     if (!__all(mx - mrun <= 8.f)) {
;       const float mn = fmaxf(mrun, mx);
;       const float alpha = __builtin_amdgcn_exp2f(mrun - mn);
;       mrun = mn; lrun *= alpha;
; #pragma unroll
;       for (int i = 0; i < 16; ++i) { o0[i] *= alpha; o1[i] *= alpha; }
;     }
.LBB0_531:
	ds_read_b128 v[48:51], v154
	ds_read_b128 v[52:55], v154 offset:32
	s_waitcnt lgkmcnt(0)
	v_mfma_f32_32x32x16_bf16 v[64:79], v[48:51], v[80:83], v[196:211]
	v_mfma_f32_32x32x16_bf16 v[64:79], v[52:55], v[84:87], v[64:79]
	ds_read_b128 v[48:51], v154 offset:64
	ds_read_b128 v[52:55], v154 offset:96
	s_waitcnt lgkmcnt(0)
	v_mfma_f32_32x32x16_bf16 v[64:79], v[48:51], v[88:91], v[64:79]
	v_mfma_f32_32x32x16_bf16 v[64:79], v[52:55], v[92:95], v[64:79]
	ds_read_b128 v[48:51], v154 offset:128
	ds_read_b128 v[52:55], v154 offset:160
	s_waitcnt lgkmcnt(0)
	v_mfma_f32_32x32x16_bf16 v[64:79], v[48:51], v[96:99], v[64:79]
	ds_read_b128 v[48:51], v154 offset:6656
	ds_read_b128 v[158:161], v154 offset:6688
	v_mfma_f32_32x32x16_bf16 v[64:79], v[52:55], v[100:103], v[64:79]
	s_waitcnt lgkmcnt(0)
	v_mfma_f32_32x32x16_bf16 v[48:63], v[48:51], v[80:83], v[196:211]
	s_nop 9
	v_max_f32_e32 v0, v64, v65
	v_max3_f32 v0, v0, v66, v67
	v_max3_f32 v0, v0, v68, v69
	v_max3_f32 v0, v0, v70, v71
	v_max3_f32 v0, v0, v72, v73
	v_mfma_f32_32x32x16_bf16 v[48:63], v[158:161], v[84:87], v[48:63]
	ds_read_b128 v[158:161], v154 offset:6720
	ds_read_b128 v[164:167], v154 offset:6752
	v_max3_f32 v0, v0, v74, v75
	v_max3_f32 v0, v0, v76, v77
	v_max3_f32 v0, v0, v78, v79
	s_waitcnt lgkmcnt(0)
	v_mfma_f32_32x32x16_bf16 v[48:63], v[158:161], v[88:91], v[48:63]
	v_mfma_f32_32x32x16_bf16 v[48:63], v[164:167], v[92:95], v[48:63]
	ds_read_b128 v[158:161], v154 offset:6784
	ds_read_b128 v[164:167], v154 offset:6816
	s_waitcnt lgkmcnt(0)
	v_mfma_f32_32x32x16_bf16 v[48:63], v[158:161], v[96:99], v[48:63]
	v_mfma_f32_32x32x16_bf16 v[48:63], v[164:167], v[100:103], v[48:63]
	s_nop 11
	v_max3_f32 v0, v0, v48, v49
	v_max3_f32 v0, v0, v50, v51
	v_max3_f32 v0, v0, v52, v53
	v_max3_f32 v0, v0, v54, v55
	v_max3_f32 v0, v0, v56, v57
	v_max3_f32 v0, v0, v58, v59
	v_max3_f32 v0, v0, v60, v61
	v_max3_f32 v0, v0, v62, v63
	v_mov_b32_e32 v158, v0
	s_nop 1
	v_permlane32_swap_b32_e32 v0, v158
	v_max_f32_e32 v0, v0, v158
	v_cmp_ge_f32_e32 vcc, s98, v0
	s_cmp_eq_u64 vcc, exec
	s_cbranch_scc1 .LBB0_533
	v_max_f32_e32 v158, s99, v0
	v_max_f32_e32 v0, 0, v158
	s_mov_b32 s98, 0x41000000
	v_exp_f32_e64 v0, -v0
	s_mov_b32 s99, 0
	v_sub_f32_e32 v196, v196, v158
	v_mul_f32_e32 v157, v157, v0
	v_pk_mul_f32 v[46:47], v[46:47], v[0:1] op_sel_hi:[1,0]
	v_pk_mul_f32 v[44:45], v[44:45], v[0:1] op_sel_hi:[1,0]
	v_pk_mul_f32 v[42:43], v[42:43], v[0:1] op_sel_hi:[1,0]
	v_pk_mul_f32 v[40:41], v[40:41], v[0:1] op_sel_hi:[1,0]
	v_pk_mul_f32 v[38:39], v[38:39], v[0:1] op_sel_hi:[1,0]
	v_pk_mul_f32 v[36:37], v[36:37], v[0:1] op_sel_hi:[1,0]
	v_pk_mul_f32 v[34:35], v[34:35], v[0:1] op_sel_hi:[1,0]
	v_pk_mul_f32 v[32:33], v[32:33], v[0:1] op_sel_hi:[1,0]
	v_pk_mul_f32 v[30:31], v[30:31], v[0:1] op_sel_hi:[1,0]
	v_pk_mul_f32 v[28:29], v[28:29], v[0:1] op_sel_hi:[1,0]
	v_pk_mul_f32 v[26:27], v[26:27], v[0:1] op_sel_hi:[1,0]
	v_pk_mul_f32 v[24:25], v[24:25], v[0:1] op_sel_hi:[1,0]
	v_pk_mul_f32 v[22:23], v[22:23], v[0:1] op_sel_hi:[1,0]
	v_pk_mul_f32 v[20:21], v[20:21], v[0:1] op_sel_hi:[1,0]
	v_pk_mul_f32 v[18:19], v[18:19], v[0:1] op_sel_hi:[1,0]
	v_pk_mul_f32 v[16:17], v[16:17], v[0:1] op_sel_hi:[1,0]
	v_mov_b32_e32 v197, v196
	v_mov_b32_e32 v198, v196
	v_mov_b32_e32 v199, v196
	v_mov_b32_e32 v200, v196
	v_mov_b32_e32 v201, v196
	v_mov_b32_e32 v202, v196
	v_mov_b32_e32 v203, v196
	v_mov_b32_e32 v204, v196
	v_mov_b32_e32 v205, v196
	v_mov_b32_e32 v206, v196
	v_mov_b32_e32 v207, v196
	v_mov_b32_e32 v208, v196
	v_mov_b32_e32 v209, v196
	v_mov_b32_e32 v210, v196
	v_mov_b32_e32 v211, v196
	v_sub_f32_e32 v64, v64, v158
	v_sub_f32_e32 v65, v65, v158
	v_sub_f32_e32 v66, v66, v158
	v_sub_f32_e32 v67, v67, v158
	v_sub_f32_e32 v68, v68, v158
	v_sub_f32_e32 v69, v69, v158
	v_sub_f32_e32 v70, v70, v158
	v_sub_f32_e32 v71, v71, v158
	v_sub_f32_e32 v72, v72, v158
	v_sub_f32_e32 v73, v73, v158
	v_sub_f32_e32 v74, v74, v158
	v_sub_f32_e32 v75, v75, v158
	v_sub_f32_e32 v76, v76, v158
	v_sub_f32_e32 v77, v77, v158
	v_sub_f32_e32 v78, v78, v158
	v_sub_f32_e32 v79, v79, v158
	v_sub_f32_e32 v48, v48, v158
	v_sub_f32_e32 v49, v49, v158
	v_sub_f32_e32 v50, v50, v158
	v_sub_f32_e32 v51, v51, v158
	v_sub_f32_e32 v52, v52, v158
	v_sub_f32_e32 v53, v53, v158
	v_sub_f32_e32 v54, v54, v158
	v_sub_f32_e32 v55, v55, v158
	v_sub_f32_e32 v56, v56, v158
	v_sub_f32_e32 v57, v57, v158
	v_sub_f32_e32 v58, v58, v158
	v_sub_f32_e32 v59, v59, v158
	v_sub_f32_e32 v60, v60, v158
	v_sub_f32_e32 v61, v61, v158
	v_sub_f32_e32 v62, v62, v158
	v_sub_f32_e32 v63, v63, v158
; DI void attn_item(const Params& p, int item, char* smem) {
;     ...
;     float ps = 0.f;
; #pragma unroll
;     for (int i = 0; i < 16; ++i) { p0[i] = __builtin_amdgcn_exp2f(p0[i] - mrun); ps += p0[i]; }
; #pragma unroll
;     for (int i = 0; i < 16; ++i) { p1[i] = __builtin_amdgcn_exp2f(p1[i] - mrun); ps += p1[i]; }
;     lrun += ps;
;     pv_step(o0, o1, Vc, r32, 0 + hi * 4, pack8<0>(p0));
;     pv_step(o0, o1, Vc, r32, 16 + hi * 4, pack8<8>(p0));
;     pv_step(o0, o1, Vc, r32, 32 + hi * 4, pack8<0>(p1));
;     pv_step(o0, o1, Vc, r32, 48 + hi * 4, pack8<8>(p1));
;     ...
;   for (int kt = 0; kt < nkt; kt += 2) {
;     if (kt + 2 < nkt) gload(b, kt + 2);
;     tile_compute(0);
;     lstore(a, 1);
;     __syncthreads();
;     if (kt + 3 < nkt) gload(a, kt + 3);
;     tile_compute(1);
;     if (kt + 2 < nkt) lstore(b, 0);
.LBB0_533:
	ds_read2_b64 v[212:215], v224 offset0:32 offset1:34
	ds_read2_b64 v[216:219], v225 offset1:2
	v_exp_f32_e32 v167, v64
	v_exp_f32_e32 v164, v65
	v_exp_f32_e32 v168, v66
	v_exp_f32_e32 v171, v67
	v_exp_f32_e32 v165, v68
	v_exp_f32_e32 v169, v69
	v_exp_f32_e32 v172, v70
	v_exp_f32_e32 v173, v71
	v_exp_f32_e32 v174, v72
	v_cvt_pk_bf16_f32 v220, v167, v164
	v_cvt_pk_bf16_f32 v221, v168, v171
	v_cvt_pk_bf16_f32 v222, v165, v169
	v_cvt_pk_bf16_f32 v223, v172, v173
	v_exp_f32_e32 v175, v73
	s_waitcnt lgkmcnt(1)
	v_mfma_f32_32x32x16_bf16 v[16:31], v[212:215], v[220:223], v[16:31]
	ds_read2_b64 v[212:215], v224 offset0:36 offset1:38
	v_exp_f32_e32 v176, v74
	v_exp_f32_e32 v0, v75
	v_exp_f32_e32 v158, v76
	s_waitcnt lgkmcnt(1)
	v_mfma_f32_32x32x16_bf16 v[32:47], v[216:219], v[220:223], v[32:47]
	ds_read2_b64 v[216:219], v225 offset0:4 offset1:6
	v_exp_f32_e32 v159, v77
	v_exp_f32_e32 v160, v78
	v_exp_f32_e32 v166, v79
	v_exp_f32_e32 v170, v48
	v_cvt_pk_bf16_f32 v220, v174, v175
	v_cvt_pk_bf16_f32 v221, v176, v0
	v_cvt_pk_bf16_f32 v222, v158, v159
	v_cvt_pk_bf16_f32 v223, v160, v166
	v_exp_f32_e32 v161, v49
	s_waitcnt lgkmcnt(1)
	v_mfma_f32_32x32x16_bf16 v[16:31], v[212:215], v[220:223], v[16:31]
	ds_read2_b64 v[212:215], v224 offset0:40 offset1:42
	v_exp_f32_e32 v177, v50
	v_exp_f32_e32 v178, v51
	v_exp_f32_e32 v179, v52
	s_waitcnt lgkmcnt(1)
	v_mfma_f32_32x32x16_bf16 v[32:47], v[216:219], v[220:223], v[32:47]
	ds_read2_b64 v[216:219], v225 offset0:8 offset1:10
	v_exp_f32_e32 v180, v53
	v_exp_f32_e32 v181, v54
	v_exp_f32_e32 v182, v55
	v_exp_f32_e32 v183, v56
	v_cvt_pk_bf16_f32 v220, v170, v161
	v_cvt_pk_bf16_f32 v221, v177, v178
	v_cvt_pk_bf16_f32 v222, v179, v180
	v_cvt_pk_bf16_f32 v223, v181, v182
	v_exp_f32_e32 v184, v57
	s_waitcnt lgkmcnt(1)
	v_mfma_f32_32x32x16_bf16 v[16:31], v[212:215], v[220:223], v[16:31]
	ds_read2_b64 v[212:215], v224 offset0:44 offset1:46
	v_exp_f32_e32 v185, v58
	v_exp_f32_e32 v187, v59
	v_exp_f32_e32 v188, v60
	s_add_i32 s12, s12, 3
	s_waitcnt lgkmcnt(1)
	v_mfma_f32_32x32x16_bf16 v[32:47], v[216:219], v[220:223], v[32:47]
	ds_read2_b64 v[216:219], v225 offset0:12 offset1:14
	v_exp_f32_e32 v186, v61
	v_exp_f32_e32 v189, v62
	v_exp_f32_e32 v190, v63
	s_waitcnt vmcnt(0)
	ds_write_b128 v150, v[104:107] offset:13312
	ds_write_b128 v151, v[108:111] offset:13312
	ds_write_b128 v152, v[112:115] offset:13312
	v_cvt_pk_bf16_f32 v220, v183, v184
	v_cvt_pk_bf16_f32 v221, v185, v187
	v_cvt_pk_bf16_f32 v222, v188, v186
	v_cvt_pk_bf16_f32 v223, v189, v190
	s_cmp_ge_u32 s12, s10
	s_waitcnt lgkmcnt(4)
	v_mfma_f32_32x32x16_bf16 v[16:31], v[212:215], v[220:223], v[16:31]
	s_waitcnt lgkmcnt(3)
	v_mfma_f32_32x32x16_bf16 v[32:47], v[216:219], v[220:223], v[32:47]
	ds_write2_b64 v226, v[116:117], v[118:119] offset1:1
	ds_write2_b64 v227, v[120:121], v[122:123] offset1:1
	s_waitcnt lgkmcnt(0)
	s_barrier
	s_cbranch_scc1 .LBB0_535
	global_load_dwordx4 v[104:107], v146, s[24:25]
	global_load_dwordx4 v[108:111], v144, s[24:25]
	global_load_dwordx4 v[112:115], v142, s[24:25]
	global_load_dwordx4 v[116:119], v140, s[26:27] offset:384
	global_load_dwordx4 v[120:123], v140, s[28:29] offset:384
.LBB0_535:
	ds_read_b128 v[10:13], v154 offset:13312
	ds_read_b128 v[48:51], v154 offset:13344
	v_add_f32_e32 v14, 0, v167
	v_add_f32_e32 v14, v164, v14
	v_add_f32_e32 v14, v168, v14
	s_waitcnt lgkmcnt(0)
	v_mfma_f32_32x32x16_bf16 v[64:79], v[10:13], v[80:83], v[196:211]
	v_add_f32_e32 v14, v171, v14
	v_add_f32_e32 v14, v165, v14
	v_add_f32_e32 v14, v169, v14
	v_add_f32_e32 v14, v172, v14
	v_add_f32_e32 v14, v173, v14
	v_add_f32_e32 v14, v174, v14
	v_add_f32_e32 v14, v175, v14
	v_mfma_f32_32x32x16_bf16 v[64:79], v[48:51], v[84:87], v[64:79]
	ds_read_b128 v[10:13], v154 offset:13376
	ds_read_b128 v[48:51], v154 offset:13408
	v_add_f32_e32 v14, v176, v14
	v_add_f32_e32 v0, v0, v14
	v_add_f32_e32 v0, v158, v0
	v_add_f32_e32 v0, v159, v0
	v_add_f32_e32 v0, v160, v0
	v_add_f32_e32 v0, v166, v0
	s_waitcnt lgkmcnt(0)
	v_mfma_f32_32x32x16_bf16 v[64:79], v[10:13], v[88:91], v[64:79]
	v_add_f32_e32 v0, v170, v0
	v_add_f32_e32 v0, v161, v0
	v_add_f32_e32 v0, v177, v0
	v_add_f32_e32 v0, v178, v0
	v_add_f32_e32 v0, v179, v0
	v_add_f32_e32 v0, v180, v0
	v_add_f32_e32 v0, v181, v0
	v_mfma_f32_32x32x16_bf16 v[64:79], v[48:51], v[92:95], v[64:79]
	ds_read_b128 v[10:13], v154 offset:13440
	ds_read_b128 v[48:51], v154 offset:13472
	v_add_f32_e32 v0, v182, v0
	v_add_f32_e32 v0, v183, v0
	v_add_f32_e32 v0, v184, v0
	v_add_f32_e32 v0, v185, v0
	v_add_f32_e32 v0, v187, v0
	v_add_f32_e32 v0, v188, v0
	s_waitcnt lgkmcnt(0)
	v_mfma_f32_32x32x16_bf16 v[64:79], v[10:13], v[96:99], v[64:79]
	ds_read_b128 v[10:13], v154 offset:19968
	ds_read_b128 v[192:195], v154 offset:20000
	v_add_f32_e32 v0, v186, v0
	v_add_f32_e32 v0, v189, v0
	v_add_f32_e32 v0, v190, v0
	v_add_f32_e32 v0, v157, v0
	ds_read_b128 v[158:161], v154 offset:20064
	v_mfma_f32_32x32x16_bf16 v[64:79], v[48:51], v[100:103], v[64:79]
	s_waitcnt lgkmcnt(0)
	v_mfma_f32_32x32x16_bf16 v[48:63], v[10:13], v[80:83], v[196:211]
	ds_read_b128 v[10:13], v154 offset:20032
	s_nop 8
	v_max_f32_e32 v14, v64, v65
	v_mfma_f32_32x32x16_bf16 v[48:63], v[192:195], v[84:87], v[48:63]
	s_waitcnt lgkmcnt(0)
	v_mfma_f32_32x32x16_bf16 v[48:63], v[10:13], v[88:91], v[48:63]
	ds_read_b128 v[10:13], v154 offset:20096
	v_mfma_f32_32x32x16_bf16 v[48:63], v[158:161], v[92:95], v[48:63]
	ds_read_b128 v[158:161], v154 offset:20128
	s_waitcnt lgkmcnt(0)
	v_mfma_f32_32x32x16_bf16 v[48:63], v[10:13], v[96:99], v[48:63]
	v_max3_f32 v10, v14, v66, v67
	v_max3_f32 v10, v10, v68, v69
	v_max3_f32 v10, v10, v70, v71
	v_max3_f32 v10, v10, v72, v73
	v_max3_f32 v10, v10, v74, v75
	v_max3_f32 v10, v10, v76, v77
	v_max3_f32 v10, v10, v78, v79
	v_mfma_f32_32x32x16_bf16 v[48:63], v[158:161], v[100:103], v[48:63]
	s_nop 11
	v_max3_f32 v10, v10, v48, v49
	v_max3_f32 v10, v10, v50, v51
	v_max3_f32 v10, v10, v52, v53
	v_max3_f32 v10, v10, v54, v55
	v_max3_f32 v10, v10, v56, v57
	v_max3_f32 v10, v10, v58, v59
	v_max3_f32 v10, v10, v60, v61
	v_max3_f32 v10, v10, v62, v63
	v_mov_b32_e32 v11, v10
	s_nop 1
	v_permlane32_swap_b32_e32 v10, v11
	v_max_f32_e32 v10, v10, v11
	v_cmp_ge_f32_e32 vcc, s98, v10
	s_cmp_eq_u64 vcc, exec
	s_cbranch_scc1 .LBB0_537
; DI void attn_item(const Params& p, int item, char* smem) {
;     ...
;       const float mn = fmaxf(mrun, mx);
;       const float alpha = __builtin_amdgcn_exp2f(mrun - mn);
;       mrun = mn; lrun *= alpha;
; #pragma unroll
;       for (int i = 0; i < 16; ++i) { o0[i] *= alpha; o1[i] *= alpha; }
;     }
;     float ps = 0.f;
; #pragma unroll
;     for (int i = 0; i < 16; ++i) { p0[i] = __builtin_amdgcn_exp2f(p0[i] - mrun); ps += p0[i]; }
; #pragma unroll
;     for (int i = 0; i < 16; ++i) { p1[i] = __builtin_amdgcn_exp2f(p1[i] - mrun); ps += p1[i]; }
;     lrun += ps;
;     pv_step(o0, o1, Vc, r32, 0 + hi * 4, pack8<0>(p0));
;     pv_step(o0, o1, Vc, r32, 16 + hi * 4, pack8<8>(p0));
;     pv_step(o0, o1, Vc, r32, 32 + hi * 4, pack8<0>(p1));
;     pv_step(o0, o1, Vc, r32, 48 + hi * 4, pack8<8>(p1));
;     ...
;     if (kt + 2 < nkt) lstore(b, 0);
;     __syncthreads();
;   }
	v_max_f32_e32 v11, s99, v10
	v_max_f32_e32 v10, 0, v11
	s_mov_b32 s98, 0x41000000
	v_exp_f32_e64 v10, -v10
	s_mov_b32 s99, 0
	v_sub_f32_e32 v196, v196, v11
	v_mul_f32_e32 v0, v0, v10
	v_pk_mul_f32 v[46:47], v[46:47], v[10:11] op_sel_hi:[1,0]
	v_pk_mul_f32 v[44:45], v[44:45], v[10:11] op_sel_hi:[1,0]
	v_pk_mul_f32 v[42:43], v[42:43], v[10:11] op_sel_hi:[1,0]
	v_pk_mul_f32 v[40:41], v[40:41], v[10:11] op_sel_hi:[1,0]
	v_pk_mul_f32 v[38:39], v[38:39], v[10:11] op_sel_hi:[1,0]
	v_pk_mul_f32 v[36:37], v[36:37], v[10:11] op_sel_hi:[1,0]
	v_pk_mul_f32 v[34:35], v[34:35], v[10:11] op_sel_hi:[1,0]
	v_pk_mul_f32 v[32:33], v[32:33], v[10:11] op_sel_hi:[1,0]
	v_pk_mul_f32 v[30:31], v[30:31], v[10:11] op_sel_hi:[1,0]
	v_pk_mul_f32 v[28:29], v[28:29], v[10:11] op_sel_hi:[1,0]
	v_pk_mul_f32 v[26:27], v[26:27], v[10:11] op_sel_hi:[1,0]
	v_pk_mul_f32 v[24:25], v[24:25], v[10:11] op_sel_hi:[1,0]
	v_pk_mul_f32 v[22:23], v[22:23], v[10:11] op_sel_hi:[1,0]
	v_pk_mul_f32 v[20:21], v[20:21], v[10:11] op_sel_hi:[1,0]
	v_pk_mul_f32 v[18:19], v[18:19], v[10:11] op_sel_hi:[1,0]
	v_pk_mul_f32 v[16:17], v[16:17], v[10:11] op_sel_hi:[1,0]
	v_mov_b32_e32 v197, v196
	v_mov_b32_e32 v198, v196
	v_mov_b32_e32 v199, v196
	v_mov_b32_e32 v200, v196
	v_mov_b32_e32 v201, v196
	v_mov_b32_e32 v202, v196
	v_mov_b32_e32 v203, v196
	v_mov_b32_e32 v204, v196
	v_mov_b32_e32 v205, v196
	v_mov_b32_e32 v206, v196
	v_mov_b32_e32 v207, v196
	v_mov_b32_e32 v208, v196
	v_mov_b32_e32 v209, v196
	v_mov_b32_e32 v210, v196
	v_mov_b32_e32 v211, v196
	v_sub_f32_e32 v64, v64, v11
	v_sub_f32_e32 v65, v65, v11
	v_sub_f32_e32 v66, v66, v11
	v_sub_f32_e32 v67, v67, v11
	v_sub_f32_e32 v68, v68, v11
	v_sub_f32_e32 v69, v69, v11
	v_sub_f32_e32 v70, v70, v11
	v_sub_f32_e32 v71, v71, v11
	v_sub_f32_e32 v72, v72, v11
	v_sub_f32_e32 v73, v73, v11
	v_sub_f32_e32 v74, v74, v11
	v_sub_f32_e32 v75, v75, v11
	v_sub_f32_e32 v76, v76, v11
	v_sub_f32_e32 v77, v77, v11
	v_sub_f32_e32 v78, v78, v11
	v_sub_f32_e32 v79, v79, v11
	v_sub_f32_e32 v48, v48, v11
	v_sub_f32_e32 v49, v49, v11
	v_sub_f32_e32 v50, v50, v11
	v_sub_f32_e32 v51, v51, v11
	v_sub_f32_e32 v52, v52, v11
	v_sub_f32_e32 v53, v53, v11
	v_sub_f32_e32 v54, v54, v11
	v_sub_f32_e32 v55, v55, v11
	v_sub_f32_e32 v56, v56, v11
	v_sub_f32_e32 v57, v57, v11
	v_sub_f32_e32 v58, v58, v11
	v_sub_f32_e32 v59, v59, v11
	v_sub_f32_e32 v60, v60, v11
	v_sub_f32_e32 v61, v61, v11
	v_sub_f32_e32 v62, v62, v11
	v_sub_f32_e32 v63, v63, v11
.LBB0_537:
	ds_read2_b64 v[212:215], v228 offset0:64 offset1:66
	ds_read2_b64 v[216:219], v229 offset0:96 offset1:98
	v_exp_f32_e32 v64, v64
	v_exp_f32_e32 v65, v65
	v_exp_f32_e32 v66, v66
	v_exp_f32_e32 v67, v67
	v_exp_f32_e32 v68, v68
	v_exp_f32_e32 v69, v69
	v_exp_f32_e32 v70, v70
	v_exp_f32_e32 v71, v71
	v_exp_f32_e32 v72, v72
	v_cvt_pk_bf16_f32 v220, v64, v65
	v_cvt_pk_bf16_f32 v221, v66, v67
	v_cvt_pk_bf16_f32 v222, v68, v69
	v_cvt_pk_bf16_f32 v223, v70, v71
	v_exp_f32_e32 v73, v73
	s_waitcnt lgkmcnt(1)
	v_mfma_f32_32x32x16_bf16 v[32:47], v[212:215], v[220:223], v[32:47]
	ds_read2_b64 v[212:215], v228 offset0:68 offset1:70
	v_exp_f32_e32 v74, v74
	v_exp_f32_e32 v75, v75
	v_exp_f32_e32 v76, v76
	s_waitcnt lgkmcnt(1)
	v_mfma_f32_32x32x16_bf16 v[16:31], v[216:219], v[220:223], v[16:31]
	ds_read2_b64 v[216:219], v229 offset0:100 offset1:102
	v_exp_f32_e32 v77, v77
	v_exp_f32_e32 v78, v78
	v_exp_f32_e32 v79, v79
	v_exp_f32_e32 v48, v48
	v_cvt_pk_bf16_f32 v220, v72, v73
	v_cvt_pk_bf16_f32 v221, v74, v75
	v_cvt_pk_bf16_f32 v222, v76, v77
	v_cvt_pk_bf16_f32 v223, v78, v79
	v_exp_f32_e32 v49, v49
	s_waitcnt lgkmcnt(1)
	v_mfma_f32_32x32x16_bf16 v[32:47], v[212:215], v[220:223], v[32:47]
	ds_read2_b64 v[212:215], v228 offset0:72 offset1:74
	v_exp_f32_e32 v50, v50
	v_exp_f32_e32 v51, v51
	v_exp_f32_e32 v52, v52
	s_waitcnt lgkmcnt(1)
	v_mfma_f32_32x32x16_bf16 v[16:31], v[216:219], v[220:223], v[16:31]
	ds_read2_b64 v[216:219], v229 offset0:104 offset1:106
	v_exp_f32_e32 v53, v53
	v_exp_f32_e32 v54, v54
	v_exp_f32_e32 v55, v55
	v_exp_f32_e32 v56, v56
	v_cvt_pk_bf16_f32 v220, v48, v49
	v_cvt_pk_bf16_f32 v221, v50, v51
	v_cvt_pk_bf16_f32 v222, v52, v53
	v_cvt_pk_bf16_f32 v223, v54, v55
	v_exp_f32_e32 v57, v57
	s_waitcnt lgkmcnt(1)
	v_mfma_f32_32x32x16_bf16 v[32:47], v[212:215], v[220:223], v[32:47]
	ds_read2_b64 v[212:215], v228 offset0:76 offset1:78
	v_exp_f32_e32 v58, v58
	v_exp_f32_e32 v59, v59
	v_exp_f32_e32 v60, v60
	s_waitcnt lgkmcnt(1)
	v_mfma_f32_32x32x16_bf16 v[16:31], v[216:219], v[220:223], v[16:31]
	ds_read2_b64 v[216:219], v229 offset0:108 offset1:110
	v_exp_f32_e32 v61, v61
	v_exp_f32_e32 v62, v62
	v_exp_f32_e32 v63, v63
	s_andn2_b64 vcc, exec, s[6:7]
	v_cvt_pk_bf16_f32 v220, v56, v57
	v_cvt_pk_bf16_f32 v221, v58, v59
	v_cvt_pk_bf16_f32 v222, v60, v61
	v_cvt_pk_bf16_f32 v223, v62, v63
	s_nop 0
	s_waitcnt lgkmcnt(1)
	v_mfma_f32_32x32x16_bf16 v[32:47], v[212:215], v[220:223], v[32:47]
	s_waitcnt lgkmcnt(0)
	v_mfma_f32_32x32x16_bf16 v[16:31], v[216:219], v[220:223], v[16:31]
	s_cbranch_vccnz .LBB0_539
	ds_write_b128 v150, v[124:127]
	ds_write_b128 v151, v[128:131]
	ds_write_b128 v152, v[132:135]
	ds_write2_b64 v139, v[2:3], v[4:5] offset1:1
	ds_write2_b64 v230, v[6:7], v[8:9] offset1:1
.LBB0_539:
	v_add_f32_e32 v10, 0, v64
	v_add_f32_e32 v10, v65, v10
	v_add_f32_e32 v10, v66, v10
	v_add_f32_e32 v10, v67, v10
	v_add_f32_e32 v10, v68, v10
	v_add_f32_e32 v10, v69, v10
	v_add_f32_e32 v10, v70, v10
	v_add_f32_e32 v10, v71, v10
	v_add_f32_e32 v10, v72, v10
	v_add_f32_e32 v10, v73, v10
	v_add_f32_e32 v10, v74, v10
	v_add_f32_e32 v10, v75, v10
	v_add_f32_e32 v10, v76, v10
	v_add_f32_e32 v10, v77, v10
	v_add_f32_e32 v10, v78, v10
	v_add_f32_e32 v10, v79, v10
	v_add_f32_e32 v10, v48, v10
	v_add_f32_e32 v10, v49, v10
	v_add_f32_e32 v10, v50, v10
	v_add_f32_e32 v10, v51, v10
	v_add_f32_e32 v10, v52, v10
	v_add_f32_e32 v10, v53, v10
	v_add_f32_e32 v10, v54, v10
	v_add_f32_e32 v10, v55, v10
	v_add_f32_e32 v10, v56, v10
	v_add_f32_e32 v10, v57, v10
	v_add_f32_e32 v10, v58, v10
	v_add_f32_e32 v10, v59, v10
	v_add_f32_e32 v10, v60, v10
	v_add_f32_e32 v10, v61, v10
	v_add_f32_e32 v10, v62, v10
	v_add_f32_e32 v10, v63, v10
	v_add_f32_e32 v157, v0, v10
	v_lshl_add_u64 v[140:141], v[140:141], 0, s[50:51]
	v_lshl_add_u64 v[142:143], v[142:143], 0, s[66:67]
	v_lshl_add_u64 v[144:145], v[144:145], 0, s[66:67]
	s_andn2_b64 vcc, exec, s[4:5]
	v_lshl_add_u64 v[146:147], v[146:147], 0, s[66:67]
	s_waitcnt lgkmcnt(0)
	s_barrier
	s_cbranch_vccz .LBB0_518
	s_mov_b32 s12, s11
	s_branch .LBB0_529

; template <int MI, int NI>
; DI void gemm256(f32x4 (&acc)[MI][NI], const u16* __restrict__ A, int lda, const u16* __restrict__ Bt, int ldb, int K, int m0, int n0, char* smem) {
;     ...
;   const int nk = K >> 5;
;   G256_ISSUE(0, 0);
;   if (nk > 1) G256_ISSUE(1, 32);
;   const int foff = lr * 64 + ((lq ^ ((lr >> 3) << 1)) * 16);
;   int st = 0;
;   for (int kt = 0; kt < nk; ++kt) {
;     if (kt + 1 < nk) asm volatile("s_waitcnt vmcnt(%0) lgkmcnt(0)" :: "n"(LPS) : "memory");
;     else asm volatile("s_waitcnt vmcnt(0) lgkmcnt(0)" ::: "memory");
;     __builtin_amdgcn_s_barrier();
;     __builtin_amdgcn_s_setprio(1);
;     const char* sb = smem + st * STAGE + foff;
;     bf16x8 af[MI], bfr[NI];
; #pragma unroll
;     for (int mi = 0; mi < MI; ++mi) af[mi] = *(const bf16x8*)(sb + (wr * MI + mi) * 1024);
; #pragma unroll
;     for (int ni = 0; ni < NI; ++ni) bfr[ni] = *(const bf16x8*)(sb + ABYTES + (wc * NI + ni) * 1024);
;     __builtin_amdgcn_sched_barrier(0x0);
;     if (kt + 2 < nk) { const int s2 = st >= 1 ? st - 1 : 2; G256_ISSUE(s2, (kt + 2) * 32); }
;     __builtin_amdgcn_s_setprio(0);
; #pragma unroll
;     for (int mi = 0; mi < MI; ++mi)
; #pragma unroll
;       for (int ni = 0; ni < NI; ++ni)
;         acc[mi][ni] = __builtin_amdgcn_mfma_f32_16x16x32_bf16(bfr[ni], af[mi], acc[mi][ni], 0, 0, 0);
;     st = st == 2 ? 0 : st + 1;
;   }
.Lpipe_mlp2:
	v_add_u32_e32 v161, s11, v160
	ds_read_b128 v[156:159], v161 offset:4096
	ds_read_b128 v[164:167], v161 offset:5120
	ds_read_b128 v[168:171], v161 offset:6144
	ds_read_b128 v[172:175], v161 offset:7168
	s_add_i32 s12, s11, 0xffffa000
	s_cmp_eq_u32 s11, 0
	s_cselect_b32 s12, 0xc000, s12
	s_add_i32 s13, s12, s0
	s_add_i32 s12, s12, s1
	s_mov_b32 m0, s13
	s_waitcnt lgkmcnt(7)
	v_mfma_f32_16x16x32_bf16 v[126:129], v[176:179], v[140:143], v[126:129]
	global_load_lds_dwordx4 v[196:197], off
	v_mfma_f32_16x16x32_bf16 v[110:113], v[176:179], v[144:147], v[110:113]
	v_lshl_add_u64 v[196:197], v[196:197], 0, s[98:99]
	s_add_i32 m0, s13, 0x400
	v_mfma_f32_16x16x32_bf16 v[94:97], v[176:179], v[148:151], v[94:97]
	global_load_lds_dwordx4 v[198:199], off
	v_mfma_f32_16x16x32_bf16 v[78:81], v[176:179], v[152:155], v[78:81]
	v_lshl_add_u64 v[198:199], v[198:199], 0, s[98:99]
	s_add_i32 m0, s13, 0x800
	s_waitcnt lgkmcnt(6)
	v_mfma_f32_16x16x32_bf16 v[122:125], v[180:183], v[140:143], v[122:125]
	global_load_lds_dwordx4 v[200:201], off
	v_mfma_f32_16x16x32_bf16 v[106:109], v[180:183], v[144:147], v[106:109]
	v_lshl_add_u64 v[200:201], v[200:201], 0, s[98:99]
	s_add_i32 m0, s13, 0xc00
	v_mfma_f32_16x16x32_bf16 v[90:93], v[180:183], v[148:151], v[90:93]
	global_load_lds_dwordx4 v[202:203], off
	v_mfma_f32_16x16x32_bf16 v[74:77], v[180:183], v[152:155], v[74:77]
	v_lshl_add_u64 v[202:203], v[202:203], 0, s[98:99]
	s_mov_b32 m0, s12
	s_waitcnt lgkmcnt(5)
	v_mfma_f32_16x16x32_bf16 v[118:121], v[184:187], v[140:143], v[118:121]
	global_load_lds_dwordx4 v[204:205], off
	v_mfma_f32_16x16x32_bf16 v[102:105], v[184:187], v[144:147], v[102:105]
	v_lshl_add_u64 v[204:205], v[204:205], 0, s[98:99]
	s_add_i32 m0, s12, 0x400
	v_mfma_f32_16x16x32_bf16 v[86:89], v[184:187], v[148:151], v[86:89]
	global_load_lds_dwordx4 v[206:207], off
	v_mfma_f32_16x16x32_bf16 v[70:73], v[184:187], v[152:155], v[70:73]
	v_lshl_add_u64 v[206:207], v[206:207], 0, s[98:99]
	s_waitcnt lgkmcnt(4)
	v_mfma_f32_16x16x32_bf16 v[114:117], v[188:191], v[140:143], v[114:117]
	v_mfma_f32_16x16x32_bf16 v[98:101], v[188:191], v[144:147], v[98:101]
	v_mfma_f32_16x16x32_bf16 v[82:85], v[188:191], v[148:151], v[82:85]
	v_mfma_f32_16x16x32_bf16 v[66:69], v[188:191], v[152:155], v[66:69]
	s_waitcnt vmcnt(6) lgkmcnt(0)
	s_barrier
	s_add_i32 s13, s11, 0x6000
	s_cmp_eq_u32 s11, 0xc000
	s_cselect_b32 s11, 0, s13
	v_add_u32_e32 v192, s11, v160
	v_add_u32_e32 v193, s11, v0
	v_mfma_f32_16x16x32_bf16 v[62:65], v[176:179], v[156:159], v[62:65]
	ds_read_b128 v[140:143], v192
	v_mfma_f32_16x16x32_bf16 v[46:49], v[176:179], v[164:167], v[46:49]
	ds_read_b128 v[144:147], v192 offset:1024
	v_mfma_f32_16x16x32_bf16 v[30:33], v[176:179], v[168:171], v[30:33]
	ds_read_b128 v[148:151], v192 offset:2048
	v_mfma_f32_16x16x32_bf16 v[14:17], v[176:179], v[172:175], v[14:17]
	ds_read_b128 v[152:155], v192 offset:3072
	ds_read_b128 v[176:179], v193 offset:16384
	v_mfma_f32_16x16x32_bf16 v[58:61], v[180:183], v[156:159], v[58:61]
	v_mfma_f32_16x16x32_bf16 v[42:45], v[180:183], v[164:167], v[42:45]
	v_mfma_f32_16x16x32_bf16 v[26:29], v[180:183], v[168:171], v[26:29]
	v_mfma_f32_16x16x32_bf16 v[10:13], v[180:183], v[172:175], v[10:13]
	ds_read_b128 v[180:183], v193 offset:17408
	v_mfma_f32_16x16x32_bf16 v[54:57], v[184:187], v[156:159], v[54:57]
	v_mfma_f32_16x16x32_bf16 v[38:41], v[184:187], v[164:167], v[38:41]
	v_mfma_f32_16x16x32_bf16 v[22:25], v[184:187], v[168:171], v[22:25]
	v_mfma_f32_16x16x32_bf16 v[6:9], v[184:187], v[172:175], v[6:9]
	ds_read_b128 v[184:187], v193 offset:18432
	v_mfma_f32_16x16x32_bf16 v[50:53], v[188:191], v[156:159], v[50:53]
	v_mfma_f32_16x16x32_bf16 v[34:37], v[188:191], v[164:167], v[34:37]
	v_mfma_f32_16x16x32_bf16 v[18:21], v[188:191], v[168:171], v[18:21]
	v_mfma_f32_16x16x32_bf16 v[2:5], v[188:191], v[172:175], v[2:5]
	ds_read_b128 v[188:191], v193 offset:19456
	s_sub_i32 s100, s100, 1
	s_cmp_lg_u32 s100, 0
	s_cbranch_scc1 .Lpipe_mlp2
	v_add_u32_e32 v161, s11, v160
	ds_read_b128 v[156:159], v161 offset:4096
	ds_read_b128 v[164:167], v161 offset:5120
	ds_read_b128 v[168:171], v161 offset:6144
	ds_read_b128 v[172:175], v161 offset:7168
	s_add_i32 s12, s11, 0xffffa000
	s_cmp_eq_u32 s11, 0
	s_cselect_b32 s12, 0xc000, s12
	s_add_i32 s13, s12, s0
	s_add_i32 s12, s12, s1
	s_mov_b32 m0, s13
	s_waitcnt lgkmcnt(7)
	v_mfma_f32_16x16x32_bf16 v[126:129], v[176:179], v[140:143], v[126:129]
	global_load_lds_dwordx4 v[196:197], off
	v_mfma_f32_16x16x32_bf16 v[110:113], v[176:179], v[144:147], v[110:113]
	v_lshl_add_u64 v[196:197], v[196:197], 0, s[98:99]
	s_add_i32 m0, s13, 0x400
	v_mfma_f32_16x16x32_bf16 v[94:97], v[176:179], v[148:151], v[94:97]
	global_load_lds_dwordx4 v[198:199], off
	v_mfma_f32_16x16x32_bf16 v[78:81], v[176:179], v[152:155], v[78:81]
	v_lshl_add_u64 v[198:199], v[198:199], 0, s[98:99]
	s_add_i32 m0, s13, 0x800
	s_waitcnt lgkmcnt(6)
	v_mfma_f32_16x16x32_bf16 v[122:125], v[180:183], v[140:143], v[122:125]
	global_load_lds_dwordx4 v[200:201], off
	v_mfma_f32_16x16x32_bf16 v[106:109], v[180:183], v[144:147], v[106:109]
	v_lshl_add_u64 v[200:201], v[200:201], 0, s[98:99]
	s_add_i32 m0, s13, 0xc00
	v_mfma_f32_16x16x32_bf16 v[90:93], v[180:183], v[148:151], v[90:93]
	global_load_lds_dwordx4 v[202:203], off
	v_mfma_f32_16x16x32_bf16 v[74:77], v[180:183], v[152:155], v[74:77]
	v_lshl_add_u64 v[202:203], v[202:203], 0, s[98:99]
	s_mov_b32 m0, s12
	s_waitcnt lgkmcnt(5)
; template <int MI, int NI>
; DI void gemm256(f32x4 (&acc)[MI][NI], const u16* __restrict__ A, int lda, const u16* __restrict__ Bt, int ldb, int K, int m0, int n0, char* smem) {
;     ...
;   const int nk = K >> 5;
;   G256_ISSUE(0, 0);
;   if (nk > 1) G256_ISSUE(1, 32);
;   const int foff = lr * 64 + ((lq ^ ((lr >> 3) << 1)) * 16);
;   int st = 0;
;   for (int kt = 0; kt < nk; ++kt) {
;     if (kt + 1 < nk) asm volatile("s_waitcnt vmcnt(%0) lgkmcnt(0)" :: "n"(LPS) : "memory");
;     else asm volatile("s_waitcnt vmcnt(0) lgkmcnt(0)" ::: "memory");
;     __builtin_amdgcn_s_barrier();
;     __builtin_amdgcn_s_setprio(1);
;     const char* sb = smem + st * STAGE + foff;
;     bf16x8 af[MI], bfr[NI];
; #pragma unroll
;     for (int mi = 0; mi < MI; ++mi) af[mi] = *(const bf16x8*)(sb + (wr * MI + mi) * 1024);
; #pragma unroll
;     for (int ni = 0; ni < NI; ++ni) bfr[ni] = *(const bf16x8*)(sb + ABYTES + (wc * NI + ni) * 1024);
;     __builtin_amdgcn_sched_barrier(0x0);
;     if (kt + 2 < nk) { const int s2 = st >= 1 ? st - 1 : 2; G256_ISSUE(s2, (kt + 2) * 32); }
;     __builtin_amdgcn_s_setprio(0);
; #pragma unroll
;     for (int mi = 0; mi < MI; ++mi)
; #pragma unroll
;       for (int ni = 0; ni < NI; ++ni)
;         acc[mi][ni] = __builtin_amdgcn_mfma_f32_16x16x32_bf16(bfr[ni], af[mi], acc[mi][ni], 0, 0, 0);
;     st = st == 2 ? 0 : st + 1;
;   }
;   asm volatile("s_waitcnt lgkmcnt(0)" ::: "memory");
;   __builtin_amdgcn_s_barrier();
	v_mfma_f32_16x16x32_bf16 v[118:121], v[184:187], v[140:143], v[118:121]
	global_load_lds_dwordx4 v[204:205], off
	v_mfma_f32_16x16x32_bf16 v[102:105], v[184:187], v[144:147], v[102:105]
	v_lshl_add_u64 v[204:205], v[204:205], 0, s[98:99]
	s_add_i32 m0, s12, 0x400
	v_mfma_f32_16x16x32_bf16 v[86:89], v[184:187], v[148:151], v[86:89]
	global_load_lds_dwordx4 v[206:207], off
	v_mfma_f32_16x16x32_bf16 v[70:73], v[184:187], v[152:155], v[70:73]
	v_lshl_add_u64 v[206:207], v[206:207], 0, s[98:99]
	s_waitcnt lgkmcnt(4)
	v_mfma_f32_16x16x32_bf16 v[114:117], v[188:191], v[140:143], v[114:117]
	v_mfma_f32_16x16x32_bf16 v[98:101], v[188:191], v[144:147], v[98:101]
	v_mfma_f32_16x16x32_bf16 v[82:85], v[188:191], v[148:151], v[82:85]
	v_mfma_f32_16x16x32_bf16 v[66:69], v[188:191], v[152:155], v[66:69]
	s_waitcnt lgkmcnt(0)
	v_mfma_f32_16x16x32_bf16 v[62:65], v[176:179], v[156:159], v[62:65]
	v_mfma_f32_16x16x32_bf16 v[46:49], v[176:179], v[164:167], v[46:49]
	v_mfma_f32_16x16x32_bf16 v[30:33], v[176:179], v[168:171], v[30:33]
	v_mfma_f32_16x16x32_bf16 v[14:17], v[176:179], v[172:175], v[14:17]
	v_mfma_f32_16x16x32_bf16 v[58:61], v[180:183], v[156:159], v[58:61]
	v_mfma_f32_16x16x32_bf16 v[42:45], v[180:183], v[164:167], v[42:45]
	v_mfma_f32_16x16x32_bf16 v[26:29], v[180:183], v[168:171], v[26:29]
	v_mfma_f32_16x16x32_bf16 v[10:13], v[180:183], v[172:175], v[10:13]
	v_mfma_f32_16x16x32_bf16 v[54:57], v[184:187], v[156:159], v[54:57]
	v_mfma_f32_16x16x32_bf16 v[38:41], v[184:187], v[164:167], v[38:41]
	v_mfma_f32_16x16x32_bf16 v[22:25], v[184:187], v[168:171], v[22:25]
	v_mfma_f32_16x16x32_bf16 v[6:9], v[184:187], v[172:175], v[6:9]
	v_mfma_f32_16x16x32_bf16 v[50:53], v[188:191], v[156:159], v[50:53]
	v_mfma_f32_16x16x32_bf16 v[34:37], v[188:191], v[164:167], v[34:37]
	v_mfma_f32_16x16x32_bf16 v[18:21], v[188:191], v[168:171], v[18:21]
	v_mfma_f32_16x16x32_bf16 v[2:5], v[188:191], v[172:175], v[2:5]
	s_mov_b32 s10, 0
	s_waitcnt vmcnt(6) lgkmcnt(0)
	s_barrier
	s_setprio 1
	s_mul_i32 s0, s10, 0x6000
	v_or_b32_e32 v0, s0, v138
	v_add_u32_e32 v136, v0, v139
	ds_read_b128 v[130:133], v136
	ds_read_b128 v[140:143], v136 offset:1024
	ds_read_b128 v[144:147], v136 offset:2048
	ds_read_b128 v[148:151], v136 offset:3072
	ds_read_b128 v[152:155], v136 offset:4096
	ds_read_b128 v[156:159], v136 offset:5120
	ds_read_b128 v[164:167], v136 offset:6144
	ds_read_b128 v[168:171], v136 offset:7168
	v_add_u32_e32 v0, v0, v135
	ds_read_b128 v[172:175], v0 offset:16384
	ds_read_b128 v[176:179], v0 offset:17408
	ds_read_b128 v[180:183], v0 offset:18432
	ds_read_b128 v[184:187], v0 offset:19456
	v_bfe_u32 v0, v134, 6, 1
	s_setprio 0
	s_waitcnt vmcnt(0) lgkmcnt(0)
	s_waitcnt lgkmcnt(3)
	v_mfma_f32_16x16x32_bf16 v[126:129], v[172:175], v[130:133], v[126:129]
	v_ashrrev_i32_e32 v160, 7, v134
	v_and_b32_e32 v161, 15, v134
	v_bfe_u32 v134, v134, 4, 2
	s_waitcnt lgkmcnt(2)
	v_mfma_f32_16x16x32_bf16 v[122:125], v[176:179], v[130:133], v[122:125]
	s_barrier
	s_waitcnt lgkmcnt(1)
	v_mfma_f32_16x16x32_bf16 v[118:121], v[180:183], v[130:133], v[118:121]
	s_waitcnt lgkmcnt(0)
	v_mfma_f32_16x16x32_bf16 v[114:117], v[184:187], v[130:133], v[114:117]
	v_mfma_f32_16x16x32_bf16 v[110:113], v[172:175], v[140:143], v[110:113]
	v_mfma_f32_16x16x32_bf16 v[106:109], v[176:179], v[140:143], v[106:109]
	v_mfma_f32_16x16x32_bf16 v[102:105], v[180:183], v[140:143], v[102:105]
	v_mfma_f32_16x16x32_bf16 v[98:101], v[184:187], v[140:143], v[98:101]
	v_mfma_f32_16x16x32_bf16 v[94:97], v[172:175], v[144:147], v[94:97]
	v_mfma_f32_16x16x32_bf16 v[90:93], v[176:179], v[144:147], v[90:93]
	v_mfma_f32_16x16x32_bf16 v[86:89], v[180:183], v[144:147], v[86:89]
	v_mfma_f32_16x16x32_bf16 v[82:85], v[184:187], v[144:147], v[82:85]
	v_mfma_f32_16x16x32_bf16 v[78:81], v[172:175], v[148:151], v[78:81]
	v_mfma_f32_16x16x32_bf16 v[130:133], v[176:179], v[148:151], v[74:77]
	v_mfma_f32_16x16x32_bf16 v[70:73], v[180:183], v[148:151], v[70:73]
	v_mfma_f32_16x16x32_bf16 v[66:69], v[184:187], v[148:151], v[66:69]
	v_mfma_f32_16x16x32_bf16 v[62:65], v[172:175], v[152:155], v[62:65]
	v_mfma_f32_16x16x32_bf16 v[58:61], v[176:179], v[152:155], v[58:61]
	v_mfma_f32_16x16x32_bf16 v[54:57], v[180:183], v[152:155], v[54:57]
	v_mfma_f32_16x16x32_bf16 v[50:53], v[184:187], v[152:155], v[50:53]
	v_mfma_f32_16x16x32_bf16 v[46:49], v[172:175], v[156:159], v[46:49]
	v_mfma_f32_16x16x32_bf16 v[42:45], v[176:179], v[156:159], v[42:45]
	v_mfma_f32_16x16x32_bf16 v[38:41], v[180:183], v[156:159], v[38:41]
	v_mfma_f32_16x16x32_bf16 v[34:37], v[184:187], v[156:159], v[34:37]
	v_mfma_f32_16x16x32_bf16 v[30:33], v[172:175], v[164:167], v[30:33]
	v_mfma_f32_16x16x32_bf16 v[26:29], v[176:179], v[164:167], v[26:29]
	v_mfma_f32_16x16x32_bf16 v[22:25], v[180:183], v[164:167], v[22:25]
	v_mfma_f32_16x16x32_bf16 v[18:21], v[184:187], v[164:167], v[18:21]
	v_mfma_f32_16x16x32_bf16 v[14:17], v[172:175], v[168:171], v[14:17]
	v_mfma_f32_16x16x32_bf16 v[10:13], v[176:179], v[168:171], v[10:13]
	v_mfma_f32_16x16x32_bf16 v[6:9], v[180:183], v[168:171], v[6:9]
	v_mfma_f32_16x16x32_bf16 v[140:143], v[184:187], v[168:171], v[2:5]
	s_setprio 1
	s_addk_i32 s0, 0x6000
	s_cmp_lg_u32 s10, 2
	s_cselect_b32 s0, s0, 0
	v_or_b32_e32 v168, s0, v138
	v_add_u32_e32 v164, v168, v139
	ds_read_b128 v[2:5], v164
	ds_read_b128 v[74:77], v164 offset:1024
	ds_read_b128 v[136:139], v164 offset:2048
	ds_read_b128 v[144:147], v164 offset:3072
	ds_read_b128 v[148:151], v164 offset:4096
	ds_read_b128 v[152:155], v164 offset:5120
	ds_read_b128 v[156:159], v164 offset:6144
	ds_read_b128 v[164:167], v164 offset:7168
	v_add_u32_e32 v135, v168, v135
	ds_read_b128 v[168:171], v135 offset:16384
	ds_read_b128 v[172:175], v135 offset:17408
	ds_read_b128 v[176:179], v135 offset:18432
	ds_read_b128 v[180:183], v135 offset:19456
	s_setprio 0
	s_waitcnt lgkmcnt(3)
	v_mfma_f32_16x16x32_bf16 v[126:129], v[168:171], v[2:5], v[126:129]
	s_waitcnt lgkmcnt(0)
	s_barrier
; template <int MI, int NI>
; DI void gemm256(f32x4 (&acc)[MI][NI], const u16* __restrict__ A, int lda, const u16* __restrict__ Bt, int ldb, int K, int m0, int n0, char* smem) {
;     ...
; #pragma unroll
;     for (int mi = 0; mi < MI; ++mi)
; #pragma unroll
;       for (int ni = 0; ni < NI; ++ni)
;         acc[mi][ni] = __builtin_amdgcn_mfma_f32_16x16x32_bf16(bfr[ni], af[mi], acc[mi][ni], 0, 0, 0);
;     st = st == 2 ? 0 : st + 1;
;   }
; template <int MI, int NI>
; DI void resid_tile(const u16* A, int K, const u16* Bt, const float* gate, const float* xl_in, const float* xc_in, float* xl_out, float* xc_out,
;                    int m0, int n0, char* smem) {
;     ...
; #pragma unroll
;   for (int mi = 0; mi < MI; ++mi) {
;     const int m = m0 + wr * 16 * MI + mi * 16 + lr;
;     const int b9 = m < NTL ? m >> 12 : 8;
;     const float* xi = xrow(xl_in, xc_in, m);
;     float* xo = m < NTL ? xl_out + (size_t)m * D : xc_out + (size_t)(m - NTL) * D;
; #pragma unroll
;     for (int ni = 0; ni < NI; ++ni) {
;       const int n = n0 + wc * 16 * NI + ni * 16 + lq * 4;
;       const float4 g = *(const float4*)(gate + (size_t)b9 * 6144 + n);
;       const float4 xv = *(const float4*)(xi + n);
;       float4 ov;
;       ov.x = xv.x + g.x * acc[mi][ni][0]; ov.y = xv.y + g.y * acc[mi][ni][1]; ov.z = xv.z + g.z * acc[mi][ni][2]; ov.w = xv.w + g.w * acc[mi][ni][3];
;       *(float4*)(xo + n) = ov;
;     }
;     __builtin_amdgcn_sched_barrier(0);
;   }
	s_waitcnt lgkmcnt(2)
	v_mfma_f32_16x16x32_bf16 v[122:125], v[172:175], v[2:5], v[122:125]
	s_waitcnt lgkmcnt(1)
	v_mfma_f32_16x16x32_bf16 v[184:187], v[176:179], v[2:5], v[118:121]
	v_lshlrev_b32_e32 v0, 6, v0
	s_waitcnt lgkmcnt(0)
	v_mfma_f32_16x16x32_bf16 v[188:191], v[180:183], v[2:5], v[114:117]
	v_lshlrev_b32_e32 v2, 7, v160
	v_mov_b32_e32 v118, s95
	v_mov_b32_e32 v119, s49
	v_add3_u32 v116, v161, s8, v2
	v_lshlrev_b32_e32 v2, 2, v134
	v_add3_u32 v2, v2, s9, v0
	v_min_i32_e32 v0, 0x8000, v116
	v_mfma_f32_16x16x32_bf16 v[110:113], v[168:171], v[74:77], v[110:113]
	v_ashrrev_i32_e32 v117, 31, v116
	v_cmp_gt_i32_e32 vcc, s58, v116
	v_mov_b32_e32 v120, s94
	v_mfma_f32_16x16x32_bf16 v[106:109], v[172:175], v[74:77], v[106:109]
	v_cndmask_b32_e32 v5, 0, v117, vcc
	v_mov_b32_e32 v121, s48
	v_cndmask_b32_e32 v115, v118, v119, vcc
	v_mfma_f32_16x16x32_bf16 v[102:105], v[176:179], v[74:77], v[102:105]
	v_cndmask_b32_e32 v114, v120, v121, vcc
	v_ashrrev_i32_e32 v3, 31, v2
	v_mfma_f32_16x16x32_bf16 v[98:101], v[180:183], v[74:77], v[98:101]
	v_mfma_f32_16x16x32_bf16 v[74:77], v[168:171], v[144:147], v[78:81]
	v_mfma_f32_16x16x32_bf16 v[78:81], v[172:175], v[144:147], v[130:133]
	s_nop 2
	v_ashrrev_i32_e32 v130, 12, v0
	v_add_u32_e32 v0, 0xffff8000, v116
	v_cndmask_b32_e32 v4, v0, v116, vcc
	v_lshlrev_b64 v[4:5], 12, v[4:5]
	v_lshl_add_u64 v[4:5], v[114:115], 0, v[4:5]
	v_mul_hi_i32_i24_e32 v115, 0x6000, v130
	v_mul_i32_i24_e32 v114, 0x6000, v130
	v_lshl_add_u64 v[130:131], s[82:83], 0, v[114:115]
	v_lshlrev_b64 v[114:115], 2, v[2:3]
	v_mfma_f32_16x16x32_bf16 v[94:97], v[168:171], v[136:139], v[94:97]
	v_lshl_add_u64 v[134:135], v[130:131], 0, v[114:115]
	v_mfma_f32_16x16x32_bf16 v[90:93], v[172:175], v[136:139], v[90:93]
	v_mfma_f32_16x16x32_bf16 v[86:89], v[176:179], v[136:139], v[86:89]
	v_mfma_f32_16x16x32_bf16 v[82:85], v[180:183], v[136:139], v[82:85]
	v_lshl_add_u64 v[136:137], v[4:5], 0, v[114:115]
	flat_load_dwordx4 v[2:5], v[134:135]
	flat_load_dwordx4 v[130:133], v[136:137]
	v_mfma_f32_16x16x32_bf16 v[70:73], v[176:179], v[144:147], v[70:73]
	v_lshlrev_b64 v[138:139], 12, v[116:117]
	v_lshl_add_u64 v[138:139], s[48:49], 0, v[138:139]
	s_waitcnt vmcnt(0) lgkmcnt(0)
	v_pk_fma_f32 v[2:3], v[126:127], v[2:3], v[130:131]
	v_mfma_f32_16x16x32_bf16 v[66:69], v[180:183], v[144:147], v[66:69]
	v_lshlrev_b64 v[144:145], 12, v[0:1]
	v_lshl_add_u64 v[144:145], s[94:95], 0, v[144:145]
	v_cndmask_b32_e32 v139, v145, v139, vcc
	v_cndmask_b32_e32 v138, v144, v138, vcc
	v_lshl_add_u64 v[138:139], v[138:139], 0, v[114:115]
	v_pk_fma_f32 v[4:5], v[128:129], v[4:5], v[132:133]
	flat_store_dwordx4 v[138:139], v[2:5]
	flat_load_dwordx4 v[126:129], v[134:135] offset:64
	flat_load_dwordx4 v[130:133], v[136:137] offset:64
	v_mfma_f32_16x16x32_bf16 v[2:5], v[172:175], v[164:167], v[10:13]
	v_mfma_f32_16x16x32_bf16 v[62:65], v[168:171], v[148:151], v[62:65]
	s_waitcnt vmcnt(0) lgkmcnt(0)
	s_nop 0
	v_pk_fma_f32 v[10:11], v[122:123], v[126:127], v[130:131]
	v_pk_fma_f32 v[12:13], v[124:125], v[128:129], v[132:133]
	flat_store_dwordx4 v[138:139], v[10:13] offset:64
	flat_load_dwordx4 v[10:13], v[134:135] offset:128
	s_nop 0
	flat_load_dwordx4 v[122:125], v[136:137] offset:128
	v_mfma_f32_16x16x32_bf16 v[58:61], v[172:175], v[148:151], v[58:61]
	s_waitcnt vmcnt(0) lgkmcnt(0)
	v_pk_fma_f32 v[10:11], v[184:185], v[10:11], v[122:123]
	v_pk_fma_f32 v[12:13], v[186:187], v[12:13], v[124:125]
	flat_store_dwordx4 v[138:139], v[10:13] offset:128
	flat_load_dwordx4 v[122:125], v[134:135] offset:192
	flat_load_dwordx4 v[126:129], v[136:137] offset:192
	v_mfma_f32_16x16x32_bf16 v[54:57], v[176:179], v[148:151], v[54:57]
	s_waitcnt vmcnt(0) lgkmcnt(0)
	v_pk_fma_f32 v[122:123], v[188:189], v[122:123], v[126:127]
	v_pk_fma_f32 v[124:125], v[190:191], v[124:125], v[128:129]
	v_mfma_f32_16x16x32_bf16 v[50:53], v[180:183], v[148:151], v[50:53]
	flat_store_dwordx4 v[138:139], v[122:125] offset:192
	v_mfma_f32_16x16x32_bf16 v[46:49], v[168:171], v[152:155], v[46:49]
	v_mfma_f32_16x16x32_bf16 v[42:45], v[172:175], v[152:155], v[42:45]
	v_mfma_f32_16x16x32_bf16 v[38:41], v[176:179], v[152:155], v[38:41]
	v_mfma_f32_16x16x32_bf16 v[34:37], v[180:183], v[152:155], v[34:37]
	v_mfma_f32_16x16x32_bf16 v[30:33], v[168:171], v[156:159], v[30:33]
	v_mfma_f32_16x16x32_bf16 v[26:29], v[172:175], v[156:159], v[26:29]
	v_mfma_f32_16x16x32_bf16 v[22:25], v[176:179], v[156:159], v[22:25]
	v_mfma_f32_16x16x32_bf16 v[18:21], v[180:183], v[156:159], v[18:21]
	v_mfma_f32_16x16x32_bf16 v[14:17], v[168:171], v[164:167], v[14:17]
	v_mfma_f32_16x16x32_bf16 v[6:9], v[176:179], v[164:167], v[6:9]
	v_mfma_f32_16x16x32_bf16 v[10:13], v[180:183], v[164:167], v[140:143]
	v_add_u32_e32 v122, 16, v116
	v_min_i32_e32 v0, 0x8000, v122
	v_cmp_gt_i32_e32 vcc, s58, v122
	v_ashrrev_i32_e32 v117, 12, v0
	v_add_u32_e32 v0, 0xffff8010, v116
	v_ashrrev_i32_e32 v123, 31, v122
	v_cndmask_b32_e32 v125, 0, v123, vcc
	v_cndmask_b32_e32 v124, v0, v122, vcc
	v_cndmask_b32_e32 v127, v118, v119, vcc
	v_cndmask_b32_e32 v126, v120, v121, vcc
	v_lshlrev_b64 v[124:125], 12, v[124:125]
	v_lshl_add_u64 v[124:125], v[126:127], 0, v[124:125]
	v_lshlrev_b64 v[122:123], 12, v[122:123]
	v_lshlrev_b64 v[126:127], 12, v[0:1]
	v_lshl_add_u64 v[122:123], s[48:49], 0, v[122:123]
	v_lshl_add_u64 v[126:127], s[94:95], 0, v[126:127]
	v_cndmask_b32_e32 v123, v127, v123, vcc
	v_cndmask_b32_e32 v122, v126, v122, vcc
	v_mul_hi_i32_i24_e32 v127, 0x6000, v117
	v_mul_i32_i24_e32 v126, 0x6000, v117
	v_lshl_add_u64 v[126:127], s[82:83], 0, v[126:127]
	v_lshl_add_u64 v[130:131], v[126:127], 0, v[114:115]
	v_lshl_add_u64 v[132:133], v[124:125], 0, v[114:115]
	v_lshl_add_u64 v[134:135], v[122:123], 0, v[114:115]
	global_load_dwordx4 v[156:159], v[130:131], off
	global_load_dwordx4 v[164:167], v[130:131], off offset:64
	global_load_dwordx4 v[168:171], v[130:131], off offset:128
	global_load_dwordx4 v[172:175], v[130:131], off offset:192
	global_load_dwordx4 v[140:143], v[132:133], off
	global_load_dwordx4 v[144:147], v[132:133], off offset:64
	global_load_dwordx4 v[148:151], v[132:133], off offset:128
	global_load_dwordx4 v[152:155], v[132:133], off offset:192
	v_mov_b32_e32 v216, 0x10000
	v_mov_b32_e32 v217, 0
	v_lshl_add_u64 v[212:213], v[132:133], 0, v[216:217]
	v_lshl_add_u64 v[214:215], v[134:135], 0, v[216:217]
	global_load_dwordx4 v[176:179], v[212:213], off
	global_load_dwordx4 v[180:183], v[212:213], off offset:64
	global_load_dwordx4 v[184:187], v[212:213], off offset:128
	global_load_dwordx4 v[188:191], v[212:213], off offset:192
	v_lshl_add_u64 v[212:213], v[212:213], 0, v[216:217]
	s_waitcnt vmcnt(4)
; template <int MI, int NI>
; DI void resid_tile(const u16* A, int K, const u16* Bt, const float* gate, const float* xl_in, const float* xc_in, float* xl_out, float* xc_out,
;                    int m0, int n0, char* smem) {
;     ...
; #pragma unroll
;   for (int mi = 0; mi < MI; ++mi) {
;     const int m = m0 + wr * 16 * MI + mi * 16 + lr;
;     const int b9 = m < NTL ? m >> 12 : 8;
;     const float* xi = xrow(xl_in, xc_in, m);
;     float* xo = m < NTL ? xl_out + (size_t)m * D : xc_out + (size_t)(m - NTL) * D;
; #pragma unroll
;     for (int ni = 0; ni < NI; ++ni) {
;       const int n = n0 + wc * 16 * NI + ni * 16 + lq * 4;
;       const float4 g = *(const float4*)(gate + (size_t)b9 * 6144 + n);
;       const float4 xv = *(const float4*)(xi + n);
;       float4 ov;
;       ov.x = xv.x + g.x * acc[mi][ni][0]; ov.y = xv.y + g.y * acc[mi][ni][1]; ov.z = xv.z + g.z * acc[mi][ni][2]; ov.w = xv.w + g.w * acc[mi][ni][3];
;       *(float4*)(xo + n) = ov;
;     }
;     __builtin_amdgcn_sched_barrier(0);
;   }
	v_pk_fma_f32 v[110:111], v[110:111], v[156:157], v[140:141]
	v_pk_fma_f32 v[112:113], v[112:113], v[158:159], v[142:143]
	v_pk_fma_f32 v[106:107], v[106:107], v[164:165], v[144:145]
	v_pk_fma_f32 v[108:109], v[108:109], v[166:167], v[146:147]
	v_pk_fma_f32 v[102:103], v[102:103], v[168:169], v[148:149]
	v_pk_fma_f32 v[104:105], v[104:105], v[170:171], v[150:151]
	v_pk_fma_f32 v[98:99], v[98:99], v[172:173], v[152:153]
	v_pk_fma_f32 v[100:101], v[100:101], v[174:175], v[154:155]
	global_store_dwordx4 v[134:135], v[110:113], off
	global_store_dwordx4 v[134:135], v[106:109], off offset:64
	global_store_dwordx4 v[134:135], v[102:105], off offset:128
	global_store_dwordx4 v[134:135], v[98:101], off offset:192
	global_load_dwordx4 v[140:143], v[212:213], off
	global_load_dwordx4 v[144:147], v[212:213], off offset:64
	global_load_dwordx4 v[148:151], v[212:213], off offset:128
	global_load_dwordx4 v[152:155], v[212:213], off offset:192
	v_lshl_add_u64 v[212:213], v[212:213], 0, v[216:217]
	s_waitcnt vmcnt(8)
	v_pk_fma_f32 v[94:95], v[94:95], v[156:157], v[176:177]
	v_pk_fma_f32 v[96:97], v[96:97], v[158:159], v[178:179]
	v_pk_fma_f32 v[90:91], v[90:91], v[164:165], v[180:181]
	v_pk_fma_f32 v[92:93], v[92:93], v[166:167], v[182:183]
	v_pk_fma_f32 v[86:87], v[86:87], v[168:169], v[184:185]
	v_pk_fma_f32 v[88:89], v[88:89], v[170:171], v[186:187]
	v_pk_fma_f32 v[82:83], v[82:83], v[172:173], v[188:189]
	v_pk_fma_f32 v[84:85], v[84:85], v[174:175], v[190:191]
	global_store_dwordx4 v[214:215], v[94:97], off
	global_store_dwordx4 v[214:215], v[90:93], off offset:64
	global_store_dwordx4 v[214:215], v[86:89], off offset:128
	global_store_dwordx4 v[214:215], v[82:85], off offset:192
	v_lshl_add_u64 v[214:215], v[214:215], 0, v[216:217]
	global_load_dwordx4 v[176:179], v[212:213], off
	global_load_dwordx4 v[180:183], v[212:213], off offset:64
	global_load_dwordx4 v[184:187], v[212:213], off offset:128
	global_load_dwordx4 v[188:191], v[212:213], off offset:192
	v_lshl_add_u64 v[212:213], v[212:213], 0, v[216:217]
	s_waitcnt vmcnt(8)
	v_pk_fma_f32 v[74:75], v[74:75], v[156:157], v[140:141]
	v_pk_fma_f32 v[76:77], v[76:77], v[158:159], v[142:143]
	v_pk_fma_f32 v[78:79], v[78:79], v[164:165], v[144:145]
	v_pk_fma_f32 v[80:81], v[80:81], v[166:167], v[146:147]
	v_pk_fma_f32 v[70:71], v[70:71], v[168:169], v[148:149]
	v_pk_fma_f32 v[72:73], v[72:73], v[170:171], v[150:151]
	v_pk_fma_f32 v[66:67], v[66:67], v[172:173], v[152:153]
	v_pk_fma_f32 v[68:69], v[68:69], v[174:175], v[154:155]
	global_store_dwordx4 v[214:215], v[74:77], off
	global_store_dwordx4 v[214:215], v[78:81], off offset:64
	global_store_dwordx4 v[214:215], v[70:73], off offset:128
	global_store_dwordx4 v[214:215], v[66:69], off offset:192
	v_lshl_add_u64 v[214:215], v[214:215], 0, v[216:217]
	global_load_dwordx4 v[140:143], v[212:213], off
	global_load_dwordx4 v[144:147], v[212:213], off offset:64
	global_load_dwordx4 v[148:151], v[212:213], off offset:128
	global_load_dwordx4 v[152:155], v[212:213], off offset:192
	v_lshl_add_u64 v[212:213], v[212:213], 0, v[216:217]
	s_waitcnt vmcnt(8)
	v_pk_fma_f32 v[62:63], v[62:63], v[156:157], v[176:177]
	v_pk_fma_f32 v[64:65], v[64:65], v[158:159], v[178:179]
	v_pk_fma_f32 v[58:59], v[58:59], v[164:165], v[180:181]
	v_pk_fma_f32 v[60:61], v[60:61], v[166:167], v[182:183]
	v_pk_fma_f32 v[54:55], v[54:55], v[168:169], v[184:185]
	v_pk_fma_f32 v[56:57], v[56:57], v[170:171], v[186:187]
	v_pk_fma_f32 v[50:51], v[50:51], v[172:173], v[188:189]
	v_pk_fma_f32 v[52:53], v[52:53], v[174:175], v[190:191]
	global_store_dwordx4 v[214:215], v[62:65], off
	global_store_dwordx4 v[214:215], v[58:61], off offset:64
	global_store_dwordx4 v[214:215], v[54:57], off offset:128
	global_store_dwordx4 v[214:215], v[50:53], off offset:192
	v_lshl_add_u64 v[214:215], v[214:215], 0, v[216:217]
	global_load_dwordx4 v[176:179], v[212:213], off
	global_load_dwordx4 v[180:183], v[212:213], off offset:64
	global_load_dwordx4 v[184:187], v[212:213], off offset:128
	global_load_dwordx4 v[188:191], v[212:213], off offset:192
	v_lshl_add_u64 v[212:213], v[212:213], 0, v[216:217]
	s_waitcnt vmcnt(8)
	v_pk_fma_f32 v[46:47], v[46:47], v[156:157], v[140:141]
	v_pk_fma_f32 v[48:49], v[48:49], v[158:159], v[142:143]
	v_pk_fma_f32 v[42:43], v[42:43], v[164:165], v[144:145]
	v_pk_fma_f32 v[44:45], v[44:45], v[166:167], v[146:147]
	v_pk_fma_f32 v[38:39], v[38:39], v[168:169], v[148:149]
	v_pk_fma_f32 v[40:41], v[40:41], v[170:171], v[150:151]
	v_pk_fma_f32 v[34:35], v[34:35], v[172:173], v[152:153]
	v_pk_fma_f32 v[36:37], v[36:37], v[174:175], v[154:155]
	global_store_dwordx4 v[214:215], v[46:49], off
	global_store_dwordx4 v[214:215], v[42:45], off offset:64
	global_store_dwordx4 v[214:215], v[38:41], off offset:128
	global_store_dwordx4 v[214:215], v[34:37], off offset:192
	v_lshl_add_u64 v[214:215], v[214:215], 0, v[216:217]
	global_load_dwordx4 v[140:143], v[212:213], off
	global_load_dwordx4 v[144:147], v[212:213], off offset:64
	global_load_dwordx4 v[148:151], v[212:213], off offset:128
	global_load_dwordx4 v[152:155], v[212:213], off offset:192
	s_waitcnt vmcnt(8)
	v_pk_fma_f32 v[30:31], v[30:31], v[156:157], v[176:177]
	v_pk_fma_f32 v[32:33], v[32:33], v[158:159], v[178:179]
	v_pk_fma_f32 v[26:27], v[26:27], v[164:165], v[180:181]
	v_pk_fma_f32 v[28:29], v[28:29], v[166:167], v[182:183]
	v_pk_fma_f32 v[22:23], v[22:23], v[168:169], v[184:185]
	v_pk_fma_f32 v[24:25], v[24:25], v[170:171], v[186:187]
	v_pk_fma_f32 v[18:19], v[18:19], v[172:173], v[188:189]
	v_pk_fma_f32 v[20:21], v[20:21], v[174:175], v[190:191]
	global_store_dwordx4 v[214:215], v[30:33], off
	global_store_dwordx4 v[214:215], v[26:29], off offset:64
	global_store_dwordx4 v[214:215], v[22:25], off offset:128
	global_store_dwordx4 v[214:215], v[18:21], off offset:192
	v_lshl_add_u64 v[214:215], v[214:215], 0, v[216:217]
	s_waitcnt vmcnt(4)
	v_pk_fma_f32 v[14:15], v[14:15], v[156:157], v[140:141]
	v_pk_fma_f32 v[16:17], v[16:17], v[158:159], v[142:143]
	v_pk_fma_f32 v[2:3], v[2:3], v[164:165], v[144:145]
	v_pk_fma_f32 v[4:5], v[4:5], v[166:167], v[146:147]
	v_pk_fma_f32 v[6:7], v[6:7], v[168:169], v[148:149]
	v_pk_fma_f32 v[8:9], v[8:9], v[170:171], v[150:151]
	v_pk_fma_f32 v[10:11], v[10:11], v[172:173], v[152:153]
	v_pk_fma_f32 v[12:13], v[12:13], v[174:175], v[154:155]
	global_store_dwordx4 v[214:215], v[14:17], off
	global_store_dwordx4 v[214:215], v[2:5], off offset:64
	global_store_dwordx4 v[214:215], v[6:9], off offset:128
	global_store_dwordx4 v[214:215], v[10:13], off offset:192
	s_add_i32 s7, s7, 1
	s_mul_i32 s0, s7, s39
	s_add_i32 s0, s0, s5
	s_cmpk_gt_i32 s0, 0x7f
	s_cbranch_scc0 .LBB0_961
